# s_setprio flips removed from the four GEMM mainloops
# speedup vs baseline: 1.0448x; 1.0119x over previous
; #define PG8_STAGE(bufoff, gbase, voff) do { _Pragma("unroll") for (int _i = 0; _i < 2; ++_i) \
;         __builtin_amdgcn_global_load_lds((const unsigned*)((const char*)(gbase) + (voff)[_i]), (LAS unsigned*)(lds + (bufoff) + ldsw + _i * 8192), 16, 0, 0); } while (0)
; #define PG8_LDA(dst, b, h) do { _Pragma("unroll") for (int m = 0; m < 4; ++m) _Pragma("unroll") for (int k = 0; k < 2; ++k) dst[m][k] = *(const LAS bf16x8*)(lds + PG8_SA(b, h) + aoff + m * 2048 + k * 1024); } while (0)
; #define PG8_LDB(dst, b, h) do { _Pragma("unroll") for (int n = 0; n < 2; ++n) _Pragma("unroll") for (int k = 0; k < 2; ++k) dst[n][k] = *(const LAS bf16x8*)(lds + PG8_SB(b, h) + boff + n * 2048 + k * 1024); } while (0)
; #define PG8_MMA(ai, bj, At, Bt) do { __builtin_amdgcn_s_setprio(1); _Pragma("unroll") for (int m = 0; m < 4; ++m) _Pragma("unroll") for (int n = 0; n < 2; ++n) _Pragma("unroll") for (int k = 0; k < 2; ++k) \
;         acc[ai][bj][m][n] = __builtin_amdgcn_mfma_f32_16x16x32_bf16(Bt[n][k], At[m][k], acc[ai][bj][m][n], 0, 0, 0); __builtin_amdgcn_s_setprio(0); } while (0)
; #define PG8_WAIT_V(n) asm volatile("s_waitcnt vmcnt(" #n ")" ::: "memory")
; #define PG8_WAIT_L(n) asm volatile("s_waitcnt lgkmcnt(" #n ")" ::: "memory")
; #define PG8_BAR __builtin_amdgcn_s_barrier()
; #define PG8_SCHED __builtin_amdgcn_sched_barrier(0)
; template <int MODE>
; __device__ __forceinline__ void gemm_phase(LAS unsigned char* lds, const Params& p, int l, int single) {
;     ...
;             PG8_LDB(B0, 0, 0); PG8_SCHED; PG8_LDA(At, 0, 0); PG8_STAGE(PG8_SA(1, 1), a1 + hstep, voffA);
;             PG8_WAIT_L(8); PG8_BAR; PG8_WAIT_L(0); PG8_MMA(0, 0, At, B0); PG8_BAR; PG8_SCHED;
;             PG8_LDB(B1, 0, 1); PG8_STAGE(PG8_SB(0, 0), b2, voffB);
;             PG8_BAR; PG8_WAIT_L(0); PG8_MMA(0, 1, At, B1); PG8_BAR;
;             PG8_LDA(At, 0, 1); PG8_STAGE(PG8_SA(0, 0), a2, voffA);
;             PG8_BAR; PG8_WAIT_L(0); PG8_MMA(1, 0, At, B0); PG8_BAR; PG8_SCHED;
;             PG8_STAGE(PG8_SB(0, 1), b2 + hstep, voffB);
;             PG8_WAIT_V(6); PG8_BAR; PG8_MMA(1, 1, At, B1); PG8_BAR;
.LBB0_181:
	s_add_u32 s20, s40, 0xfff80080
	s_addc_u32 s21, s41, -1
	s_add_i32 s23, 0, 0x10000
	v_add_u32_e32 v142, s23, v181
	ds_read_b128 v[130:133], v142
	ds_read_b128 v[174:177], v142 offset:1024
	ds_read_b128 v[184:187], v142 offset:2048
	ds_read_b128 v[188:191], v142 offset:3072
	s_cmp_eq_u32 s22, 28
	s_cselect_b32 s79, s1, s21
	s_cselect_b32 s78, s0, s20
	s_cselect_b32 s21, s19, s17
	s_cselect_b32 s20, s18, s15
	v_lshl_add_u64 v[178:179], s[40:41], 0, v[170:171]
	s_add_i32 m0, s84, 0xc000
	ds_read_b128 v[192:195], v161
	ds_read_b128 v[196:199], v161 offset:1024
	ds_read_b128 v[208:211], v161 offset:2048
	ds_read_b128 v[212:215], v161 offset:3072
	ds_read_b128 v[216:219], v161 offset:4096
	ds_read_b128 v[220:223], v161 offset:5120
	ds_read_b128 v[224:227], v161 offset:6144
	ds_read_b128 v[228:231], v161 offset:7168
	global_load_lds_dwordx4 v[178:179], off
	v_lshl_add_u64 v[178:179], s[40:41], 0, v[172:173]
	s_add_i32 m0, s84, 0xe000
	s_nop 0
	global_load_lds_dwordx4 v[178:179], off
	s_waitcnt lgkmcnt(8)
	s_barrier
	s_waitcnt lgkmcnt(0)
	s_waitcnt lgkmcnt(0)
	v_mfma_f32_16x16x32_bf16 v[126:129], v[130:133], v[192:195], v[126:129]
	v_mfma_f32_16x16x32_bf16 v[122:125], v[184:187], v[192:195], v[122:125]
	v_mfma_f32_16x16x32_bf16 v[118:121], v[130:133], v[208:211], v[118:121]
	v_mfma_f32_16x16x32_bf16 v[114:117], v[184:187], v[208:211], v[114:117]
	v_mfma_f32_16x16x32_bf16 v[110:113], v[130:133], v[216:219], v[110:113]
	v_mfma_f32_16x16x32_bf16 v[106:109], v[184:187], v[216:219], v[106:109]
	v_mfma_f32_16x16x32_bf16 v[102:105], v[130:133], v[224:227], v[102:105]
	v_mfma_f32_16x16x32_bf16 v[98:101], v[184:187], v[224:227], v[98:101]
	v_mfma_f32_16x16x32_bf16 v[126:129], v[174:177], v[196:199], v[126:129]
	v_mfma_f32_16x16x32_bf16 v[122:125], v[188:191], v[196:199], v[122:125]
	v_mfma_f32_16x16x32_bf16 v[118:121], v[174:177], v[212:215], v[118:121]
	v_mfma_f32_16x16x32_bf16 v[114:117], v[188:191], v[212:215], v[114:117]
	v_mfma_f32_16x16x32_bf16 v[110:113], v[174:177], v[220:223], v[110:113]
	v_mfma_f32_16x16x32_bf16 v[106:109], v[188:191], v[220:223], v[106:109]
	v_mfma_f32_16x16x32_bf16 v[102:105], v[174:177], v[228:231], v[102:105]
	v_mfma_f32_16x16x32_bf16 v[98:101], v[188:191], v[228:231], v[98:101]
	s_barrier
	s_add_i32 vcc_lo, 0, 0x14000
	s_add_i32 s23, s23, s76
	v_add_u32_e32 v142, vcc_lo, v181
	v_lshl_add_u64 v[178:179], s[20:21], 0, v[148:149]
	s_mov_b32 m0, s23
	ds_read_b128 v[232:235], v142
	ds_read_b128 v[236:239], v142 offset:1024
	ds_read_b128 v[240:243], v142 offset:2048
	ds_read_b128 v[244:247], v142 offset:3072
	global_load_lds_dwordx4 v[178:179], off
	v_lshl_add_u64 v[248:249], s[20:21], 0, v[152:153]
	s_add_i32 m0, s23, 0x2000
	s_nop 0
	global_load_lds_dwordx4 v[248:249], off
	s_barrier
	s_waitcnt lgkmcnt(0)
	s_waitcnt lgkmcnt(0)
	v_mfma_f32_16x16x32_bf16 v[62:65], v[232:235], v[192:195], v[62:65]
	v_mfma_f32_16x16x32_bf16 v[58:61], v[240:243], v[192:195], v[58:61]
	v_mfma_f32_16x16x32_bf16 v[54:57], v[232:235], v[208:211], v[54:57]
	v_mfma_f32_16x16x32_bf16 v[50:53], v[240:243], v[208:211], v[50:53]
	v_mfma_f32_16x16x32_bf16 v[46:49], v[232:235], v[216:219], v[46:49]
	v_mfma_f32_16x16x32_bf16 v[42:45], v[240:243], v[216:219], v[42:45]
	v_mfma_f32_16x16x32_bf16 v[38:41], v[232:235], v[224:227], v[38:41]
	v_mfma_f32_16x16x32_bf16 v[34:37], v[240:243], v[224:227], v[34:37]
	v_mfma_f32_16x16x32_bf16 v[62:65], v[236:239], v[196:199], v[62:65]
	v_mfma_f32_16x16x32_bf16 v[58:61], v[244:247], v[196:199], v[58:61]
	v_mfma_f32_16x16x32_bf16 v[54:57], v[236:239], v[212:215], v[54:57]
	v_mfma_f32_16x16x32_bf16 v[50:53], v[244:247], v[212:215], v[50:53]
	v_mfma_f32_16x16x32_bf16 v[46:49], v[236:239], v[220:223], v[46:49]
	v_mfma_f32_16x16x32_bf16 v[42:45], v[244:247], v[220:223], v[42:45]
	v_mfma_f32_16x16x32_bf16 v[38:41], v[236:239], v[228:231], v[38:41]
	v_mfma_f32_16x16x32_bf16 v[34:37], v[244:247], v[228:231], v[34:37]
	s_mov_b32 m0, s84
	v_lshl_add_u64 v[250:251], s[78:79], 0, v[146:147]
	s_barrier
	ds_read_b128 v[192:195], v161 offset:16384
	ds_read_b128 v[196:199], v161 offset:17408
	ds_read_b128 v[208:211], v161 offset:18432
	ds_read_b128 v[212:215], v161 offset:19456
	ds_read_b128 v[216:219], v161 offset:20480
	ds_read_b128 v[220:223], v161 offset:21504
	ds_read_b128 v[224:227], v161 offset:22528
	ds_read_b128 v[228:231], v161 offset:23552
	global_load_lds_dwordx4 v[250:251], off
	v_lshl_add_u64 v[142:143], s[78:79], 0, v[150:151]
	s_mov_b32 m0, s85
	s_nop 0
	global_load_lds_dwordx4 v[142:143], off
	s_barrier
	s_waitcnt lgkmcnt(0)
	s_waitcnt lgkmcnt(0)
	v_mfma_f32_16x16x32_bf16 v[94:97], v[130:133], v[192:195], v[94:97]
	v_mfma_f32_16x16x32_bf16 v[90:93], v[184:187], v[192:195], v[90:93]
	v_mfma_f32_16x16x32_bf16 v[86:89], v[130:133], v[208:211], v[86:89]
	v_mfma_f32_16x16x32_bf16 v[82:85], v[184:187], v[208:211], v[82:85]
	v_mfma_f32_16x16x32_bf16 v[78:81], v[130:133], v[216:219], v[78:81]
	v_mfma_f32_16x16x32_bf16 v[74:77], v[184:187], v[216:219], v[74:77]
	v_mfma_f32_16x16x32_bf16 v[70:73], v[130:133], v[224:227], v[70:73]
	v_mfma_f32_16x16x32_bf16 v[66:69], v[184:187], v[224:227], v[66:69]
	v_mfma_f32_16x16x32_bf16 v[94:97], v[174:177], v[196:199], v[94:97]
	v_mfma_f32_16x16x32_bf16 v[90:93], v[188:191], v[196:199], v[90:93]
	v_mfma_f32_16x16x32_bf16 v[86:89], v[174:177], v[212:215], v[86:89]
	v_mfma_f32_16x16x32_bf16 v[82:85], v[188:191], v[212:215], v[82:85]
	v_mfma_f32_16x16x32_bf16 v[78:81], v[174:177], v[220:223], v[78:81]
	v_mfma_f32_16x16x32_bf16 v[74:77], v[188:191], v[220:223], v[74:77]
	v_mfma_f32_16x16x32_bf16 v[70:73], v[174:177], v[228:231], v[70:73]
	v_mfma_f32_16x16x32_bf16 v[66:69], v[188:191], v[228:231], v[66:69]
	s_barrier
; #define PG8_STAGE(bufoff, gbase, voff) do { _Pragma("unroll") for (int _i = 0; _i < 2; ++_i) \
;         __builtin_amdgcn_global_load_lds((const unsigned*)((const char*)(gbase) + (voff)[_i]), (LAS unsigned*)(lds + (bufoff) + ldsw + _i * 8192), 16, 0, 0); } while (0)
; #define PG8_LDA(dst, b, h) do { _Pragma("unroll") for (int m = 0; m < 4; ++m) _Pragma("unroll") for (int k = 0; k < 2; ++k) dst[m][k] = *(const LAS bf16x8*)(lds + PG8_SA(b, h) + aoff + m * 2048 + k * 1024); } while (0)
; #define PG8_LDB(dst, b, h) do { _Pragma("unroll") for (int n = 0; n < 2; ++n) _Pragma("unroll") for (int k = 0; k < 2; ++k) dst[n][k] = *(const LAS bf16x8*)(lds + PG8_SB(b, h) + boff + n * 2048 + k * 1024); } while (0)
; #define PG8_MMA(ai, bj, At, Bt) do { __builtin_amdgcn_s_setprio(1); _Pragma("unroll") for (int m = 0; m < 4; ++m) _Pragma("unroll") for (int n = 0; n < 2; ++n) _Pragma("unroll") for (int k = 0; k < 2; ++k) \
;         acc[ai][bj][m][n] = __builtin_amdgcn_mfma_f32_16x16x32_bf16(Bt[n][k], At[m][k], acc[ai][bj][m][n], 0, 0, 0); __builtin_amdgcn_s_setprio(0); } while (0)
; #define PG8_WAIT_V(n) asm volatile("s_waitcnt vmcnt(" #n ")" ::: "memory")
; #define PG8_WAIT_L(n) asm volatile("s_waitcnt lgkmcnt(" #n ")" ::: "memory")
; #define PG8_BAR __builtin_amdgcn_s_barrier()
; #define PG8_SCHED __builtin_amdgcn_sched_barrier(0)
; template <int MODE>
; __device__ __forceinline__ void gemm_phase(LAS unsigned char* lds, const Params& p, int l, int single) {
;     ...
;             PG8_STAGE(PG8_SB(0, 1), b2 + hstep, voffB);
;             PG8_WAIT_V(6); PG8_BAR; PG8_MMA(1, 1, At, B1); PG8_BAR;
;             PG8_LDB(B0, 1, 0); PG8_SCHED; PG8_LDA(At, 1, 0); PG8_STAGE(PG8_SA(0, 1), a2 + hstep, voffA);
;             PG8_WAIT_L(8); PG8_BAR; PG8_WAIT_L(0); PG8_MMA(0, 0, At, B0); PG8_BAR; PG8_SCHED;
;             PG8_LDB(B1, 1, 1); PG8_STAGE(PG8_SB(1, 0), b3, voffB);
;             PG8_BAR; PG8_WAIT_L(0); PG8_MMA(0, 1, At, B1); PG8_BAR;
;             PG8_LDA(At, 1, 1); PG8_STAGE(PG8_SA(1, 0), a3, voffA);
	s_add_u32 s28, s20, 0x80000
	s_addc_u32 s29, s21, 0
	s_add_i32 s23, vcc_lo, s76
	v_lshl_add_u64 v[130:131], s[28:29], 0, v[148:149]
	s_mov_b32 m0, s23
	s_nop 0
	global_load_lds_dwordx4 v[130:131], off
	v_lshl_add_u64 v[130:131], s[28:29], 0, v[152:153]
	s_add_i32 m0, s23, 0x2000
	s_nop 0
	global_load_lds_dwordx4 v[130:131], off
	s_waitcnt vmcnt(6)
	s_barrier
	v_mfma_f32_16x16x32_bf16 v[30:33], v[232:235], v[192:195], v[30:33]
	v_mfma_f32_16x16x32_bf16 v[26:29], v[240:243], v[192:195], v[26:29]
	v_mfma_f32_16x16x32_bf16 v[22:25], v[232:235], v[208:211], v[22:25]
	v_mfma_f32_16x16x32_bf16 v[18:21], v[240:243], v[208:211], v[18:21]
	v_mfma_f32_16x16x32_bf16 v[14:17], v[232:235], v[216:219], v[14:17]
	v_mfma_f32_16x16x32_bf16 v[10:13], v[240:243], v[216:219], v[10:13]
	v_mfma_f32_16x16x32_bf16 v[6:9], v[232:235], v[224:227], v[6:9]
	v_mfma_f32_16x16x32_bf16 v[2:5], v[240:243], v[224:227], v[2:5]
	v_mfma_f32_16x16x32_bf16 v[30:33], v[236:239], v[196:199], v[30:33]
	v_mfma_f32_16x16x32_bf16 v[26:29], v[244:247], v[196:199], v[26:29]
	v_mfma_f32_16x16x32_bf16 v[22:25], v[236:239], v[212:215], v[22:25]
	v_mfma_f32_16x16x32_bf16 v[18:21], v[244:247], v[212:215], v[18:21]
	v_mfma_f32_16x16x32_bf16 v[14:17], v[236:239], v[220:223], v[14:17]
	v_mfma_f32_16x16x32_bf16 v[10:13], v[244:247], v[220:223], v[10:13]
	v_mfma_f32_16x16x32_bf16 v[6:9], v[236:239], v[228:231], v[6:9]
	v_mfma_f32_16x16x32_bf16 v[2:5], v[244:247], v[228:231], v[2:5]
	s_add_i32 s23, 0, 0x18000
	v_add_u32_e32 v155, s23, v181
	s_barrier
	ds_read_b128 v[130:133], v155
	ds_read_b128 v[174:177], v155 offset:1024
	ds_read_b128 v[184:187], v155 offset:2048
	ds_read_b128 v[188:191], v155 offset:3072
	s_add_u32 s28, s78, 0x80000
	s_addc_u32 s29, s79, 0
	s_mov_b32 m0, s90
	v_lshl_add_u64 v[232:233], s[28:29], 0, v[146:147]
	ds_read_b128 v[192:195], v161 offset:32768
	ds_read_b128 v[196:199], v161 offset:33792
	ds_read_b128 v[208:211], v161 offset:34816
	ds_read_b128 v[212:215], v161 offset:35840
	ds_read_b128 v[216:219], v161 offset:36864
	ds_read_b128 v[220:223], v161 offset:37888
	ds_read_b128 v[224:227], v161 offset:38912
	ds_read_b128 v[228:231], v161 offset:39936
	global_load_lds_dwordx4 v[232:233], off
	v_lshl_add_u64 v[232:233], s[28:29], 0, v[150:151]
	s_mov_b32 m0, s97
	s_nop 0
	global_load_lds_dwordx4 v[232:233], off
	s_waitcnt lgkmcnt(8)
	s_barrier
	s_waitcnt lgkmcnt(0)
	s_waitcnt lgkmcnt(0)
	v_mfma_f32_16x16x32_bf16 v[126:129], v[130:133], v[192:195], v[126:129]
	v_mfma_f32_16x16x32_bf16 v[122:125], v[184:187], v[192:195], v[122:125]
	v_mfma_f32_16x16x32_bf16 v[118:121], v[130:133], v[208:211], v[118:121]
	v_mfma_f32_16x16x32_bf16 v[114:117], v[184:187], v[208:211], v[114:117]
	v_mfma_f32_16x16x32_bf16 v[110:113], v[130:133], v[216:219], v[110:113]
	v_mfma_f32_16x16x32_bf16 v[106:109], v[184:187], v[216:219], v[106:109]
	v_mfma_f32_16x16x32_bf16 v[102:105], v[130:133], v[224:227], v[102:105]
	v_mfma_f32_16x16x32_bf16 v[98:101], v[184:187], v[224:227], v[98:101]
	v_mfma_f32_16x16x32_bf16 v[126:129], v[174:177], v[196:199], v[126:129]
	v_mfma_f32_16x16x32_bf16 v[122:125], v[188:191], v[196:199], v[122:125]
	v_mfma_f32_16x16x32_bf16 v[118:121], v[174:177], v[212:215], v[118:121]
	v_mfma_f32_16x16x32_bf16 v[114:117], v[188:191], v[212:215], v[114:117]
	v_mfma_f32_16x16x32_bf16 v[110:113], v[174:177], v[220:223], v[110:113]
	v_mfma_f32_16x16x32_bf16 v[106:109], v[188:191], v[220:223], v[106:109]
	v_mfma_f32_16x16x32_bf16 v[102:105], v[174:177], v[228:231], v[102:105]
	v_mfma_f32_16x16x32_bf16 v[98:101], v[188:191], v[228:231], v[98:101]
	s_barrier
	s_add_i32 s28, 0, 0x1c000
	s_add_i32 s23, s23, s76
	v_add_u32_e32 v155, s28, v181
	v_lshl_add_u64 v[178:179], v[178:179], 0, s[94:95]
	s_mov_b32 m0, s23
	ds_read_b128 v[232:235], v155
	ds_read_b128 v[236:239], v155 offset:1024
	ds_read_b128 v[240:243], v155 offset:2048
	ds_read_b128 v[244:247], v155 offset:3072
	global_load_lds_dwordx4 v[178:179], off
	v_lshl_add_u64 v[178:179], v[248:249], 0, s[94:95]
	s_add_i32 m0, s23, 0x2000
	s_nop 0
	global_load_lds_dwordx4 v[178:179], off
	s_barrier
; #define PG8_STAGE(bufoff, gbase, voff) do { _Pragma("unroll") for (int _i = 0; _i < 2; ++_i) \
;         __builtin_amdgcn_global_load_lds((const unsigned*)((const char*)(gbase) + (voff)[_i]), (LAS unsigned*)(lds + (bufoff) + ldsw + _i * 8192), 16, 0, 0); } while (0)
; #define PG8_LDA(dst, b, h) do { _Pragma("unroll") for (int m = 0; m < 4; ++m) _Pragma("unroll") for (int k = 0; k < 2; ++k) dst[m][k] = *(const LAS bf16x8*)(lds + PG8_SA(b, h) + aoff + m * 2048 + k * 1024); } while (0)
; #define PG8_MMA(ai, bj, At, Bt) do { __builtin_amdgcn_s_setprio(1); _Pragma("unroll") for (int m = 0; m < 4; ++m) _Pragma("unroll") for (int n = 0; n < 2; ++n) _Pragma("unroll") for (int k = 0; k < 2; ++k) \
;         acc[ai][bj][m][n] = __builtin_amdgcn_mfma_f32_16x16x32_bf16(Bt[n][k], At[m][k], acc[ai][bj][m][n], 0, 0, 0); __builtin_amdgcn_s_setprio(0); } while (0)
; #define PG8_WAIT_V(n) asm volatile("s_waitcnt vmcnt(" #n ")" ::: "memory")
; #define PG8_WAIT_L(n) asm volatile("s_waitcnt lgkmcnt(" #n ")" ::: "memory")
; #define PG8_BAR __builtin_amdgcn_s_barrier()
; #define PG8_SCHED __builtin_amdgcn_sched_barrier(0)
; template <int MODE>
; __device__ __forceinline__ void gemm_phase(LAS unsigned char* lds, const Params& p, int l, int single) {
;     ...
;             PG8_BAR; PG8_WAIT_L(0); PG8_MMA(0, 1, At, B1); PG8_BAR;
;             PG8_LDA(At, 1, 1); PG8_STAGE(PG8_SA(1, 0), a3, voffA);
;             PG8_BAR; PG8_WAIT_L(0); PG8_MMA(1, 0, At, B0); PG8_BAR; PG8_SCHED;
;             PG8_STAGE(PG8_SB(1, 1), b3 + hstep, voffB);
;             PG8_WAIT_V(6); PG8_BAR; PG8_MMA(1, 1, At, B1); PG8_BAR;
	s_waitcnt lgkmcnt(0)
	s_waitcnt lgkmcnt(0)
	v_mfma_f32_16x16x32_bf16 v[62:65], v[232:235], v[192:195], v[62:65]
	v_mfma_f32_16x16x32_bf16 v[58:61], v[240:243], v[192:195], v[58:61]
	v_mfma_f32_16x16x32_bf16 v[54:57], v[232:235], v[208:211], v[54:57]
	v_mfma_f32_16x16x32_bf16 v[50:53], v[240:243], v[208:211], v[50:53]
	v_mfma_f32_16x16x32_bf16 v[46:49], v[232:235], v[216:219], v[46:49]
	v_mfma_f32_16x16x32_bf16 v[42:45], v[240:243], v[216:219], v[42:45]
	v_mfma_f32_16x16x32_bf16 v[38:41], v[232:235], v[224:227], v[38:41]
	v_mfma_f32_16x16x32_bf16 v[34:37], v[240:243], v[224:227], v[34:37]
	v_mfma_f32_16x16x32_bf16 v[62:65], v[236:239], v[196:199], v[62:65]
	v_mfma_f32_16x16x32_bf16 v[58:61], v[244:247], v[196:199], v[58:61]
	v_mfma_f32_16x16x32_bf16 v[54:57], v[236:239], v[212:215], v[54:57]
	v_mfma_f32_16x16x32_bf16 v[50:53], v[244:247], v[212:215], v[50:53]
	v_mfma_f32_16x16x32_bf16 v[46:49], v[236:239], v[220:223], v[46:49]
	v_mfma_f32_16x16x32_bf16 v[42:45], v[244:247], v[220:223], v[42:45]
	v_mfma_f32_16x16x32_bf16 v[38:41], v[236:239], v[228:231], v[38:41]
	v_mfma_f32_16x16x32_bf16 v[34:37], v[244:247], v[228:231], v[34:37]
	s_mov_b32 m0, s24
	v_lshl_add_u64 v[178:179], v[250:251], 0, s[94:95]
	s_barrier
	ds_read_b128 v[192:195], v161 offset:49152
	ds_read_b128 v[196:199], v161 offset:50176
	ds_read_b128 v[208:211], v161 offset:51200
	ds_read_b128 v[212:215], v161 offset:52224
	ds_read_b128 v[216:219], v161 offset:53248
	ds_read_b128 v[220:223], v161 offset:54272
	ds_read_b128 v[224:227], v161 offset:55296
	ds_read_b128 v[228:231], v161 offset:56320
	global_load_lds_dwordx4 v[178:179], off
	v_lshl_add_u64 v[142:143], v[142:143], 0, s[94:95]
	s_mov_b32 m0, s33
	s_nop 0
	global_load_lds_dwordx4 v[142:143], off
	s_barrier
	s_waitcnt lgkmcnt(0)
	s_waitcnt lgkmcnt(0)
	v_mfma_f32_16x16x32_bf16 v[94:97], v[130:133], v[192:195], v[94:97]
	v_mfma_f32_16x16x32_bf16 v[90:93], v[184:187], v[192:195], v[90:93]
	v_mfma_f32_16x16x32_bf16 v[86:89], v[130:133], v[208:211], v[86:89]
	v_mfma_f32_16x16x32_bf16 v[82:85], v[184:187], v[208:211], v[82:85]
	v_mfma_f32_16x16x32_bf16 v[78:81], v[130:133], v[216:219], v[78:81]
	v_mfma_f32_16x16x32_bf16 v[74:77], v[184:187], v[216:219], v[74:77]
	v_mfma_f32_16x16x32_bf16 v[70:73], v[130:133], v[224:227], v[70:73]
	v_mfma_f32_16x16x32_bf16 v[66:69], v[184:187], v[224:227], v[66:69]
	v_mfma_f32_16x16x32_bf16 v[94:97], v[174:177], v[196:199], v[94:97]
	v_mfma_f32_16x16x32_bf16 v[90:93], v[188:191], v[196:199], v[90:93]
	v_mfma_f32_16x16x32_bf16 v[86:89], v[174:177], v[212:215], v[86:89]
	v_mfma_f32_16x16x32_bf16 v[82:85], v[188:191], v[212:215], v[82:85]
	v_mfma_f32_16x16x32_bf16 v[78:81], v[174:177], v[220:223], v[78:81]
	v_mfma_f32_16x16x32_bf16 v[74:77], v[188:191], v[220:223], v[74:77]
	v_mfma_f32_16x16x32_bf16 v[70:73], v[174:177], v[228:231], v[70:73]
	v_mfma_f32_16x16x32_bf16 v[66:69], v[188:191], v[228:231], v[66:69]
	s_barrier
	s_add_u32 s20, s20, 0x80080
	s_addc_u32 s21, s21, 0
	s_add_i32 s23, s28, s76
	v_lshl_add_u64 v[130:131], s[20:21], 0, v[148:149]
	s_mov_b32 m0, s23
	s_nop 0
	global_load_lds_dwordx4 v[130:131], off
	v_lshl_add_u64 v[130:131], s[20:21], 0, v[152:153]
	s_add_i32 m0, s23, 0x2000
	s_nop 0
	global_load_lds_dwordx4 v[130:131], off
	s_waitcnt vmcnt(6)
	s_barrier
	v_mfma_f32_16x16x32_bf16 v[30:33], v[232:235], v[192:195], v[30:33]
	v_mfma_f32_16x16x32_bf16 v[26:29], v[240:243], v[192:195], v[26:29]
	v_mfma_f32_16x16x32_bf16 v[22:25], v[232:235], v[208:211], v[22:25]
	v_mfma_f32_16x16x32_bf16 v[18:21], v[240:243], v[208:211], v[18:21]
	v_mfma_f32_16x16x32_bf16 v[14:17], v[232:235], v[216:219], v[14:17]
	v_mfma_f32_16x16x32_bf16 v[10:13], v[240:243], v[216:219], v[10:13]
	v_mfma_f32_16x16x32_bf16 v[6:9], v[232:235], v[224:227], v[6:9]
	v_mfma_f32_16x16x32_bf16 v[2:5], v[240:243], v[224:227], v[2:5]
	v_mfma_f32_16x16x32_bf16 v[30:33], v[236:239], v[196:199], v[30:33]
	v_mfma_f32_16x16x32_bf16 v[26:29], v[244:247], v[196:199], v[26:29]
	v_mfma_f32_16x16x32_bf16 v[22:25], v[236:239], v[212:215], v[22:25]
	v_mfma_f32_16x16x32_bf16 v[18:21], v[244:247], v[212:215], v[18:21]
	v_mfma_f32_16x16x32_bf16 v[14:17], v[236:239], v[220:223], v[14:17]
	v_mfma_f32_16x16x32_bf16 v[10:13], v[244:247], v[220:223], v[10:13]
	v_mfma_f32_16x16x32_bf16 v[6:9], v[236:239], v[228:231], v[6:9]
	v_mfma_f32_16x16x32_bf16 v[2:5], v[244:247], v[228:231], v[2:5]
	s_add_i32 s22, s22, 2
	s_add_u32 s40, s40, 0x100
	s_addc_u32 s41, s41, 0
	s_add_u32 s15, s15, 0x100
	s_addc_u32 s17, s17, 0
	s_cmp_gt_u32 s22, 29
	s_barrier
	s_cbranch_scc0 .LBB0_181
	s_and_b32 s15, s96, -4
	s_cmp_lt_i32 s15, 16
	s_cbranch_scc1 .LBB0_184
	s_cmp_lg_u32 s15, 16
	s_mov_b64 s[20:21], -1
	s_cselect_b64 s[22:23], -1, 0
	s_cbranch_execz .LBB0_185
	s_branch .LBB0_186

; #define PG8_STAGE(bufoff, gbase, voff) do { _Pragma("unroll") for (int _i = 0; _i < 2; ++_i) \
;         __builtin_amdgcn_global_load_lds((const unsigned*)((const char*)(gbase) + (voff)[_i]), (LAS unsigned*)(lds + (bufoff) + ldsw + _i * 8192), 16, 0, 0); } while (0)
; #define PG8_LDA(dst, b, h) do { _Pragma("unroll") for (int m = 0; m < 4; ++m) _Pragma("unroll") for (int k = 0; k < 2; ++k) dst[m][k] = *(const LAS bf16x8*)(lds + PG8_SA(b, h) + aoff + m * 2048 + k * 1024); } while (0)
; #define PG8_LDB(dst, b, h) do { _Pragma("unroll") for (int n = 0; n < 2; ++n) _Pragma("unroll") for (int k = 0; k < 2; ++k) dst[n][k] = *(const LAS bf16x8*)(lds + PG8_SB(b, h) + boff + n * 2048 + k * 1024); } while (0)
; #define PG8_MMA(ai, bj, At, Bt) do { __builtin_amdgcn_s_setprio(1); _Pragma("unroll") for (int m = 0; m < 4; ++m) _Pragma("unroll") for (int n = 0; n < 2; ++n) _Pragma("unroll") for (int k = 0; k < 2; ++k) \
;         acc[ai][bj][m][n] = __builtin_amdgcn_mfma_f32_16x16x32_bf16(Bt[n][k], At[m][k], acc[ai][bj][m][n], 0, 0, 0); __builtin_amdgcn_s_setprio(0); } while (0)
; #define PG8_WAIT_V(n) asm volatile("s_waitcnt vmcnt(" #n ")" ::: "memory")
; #define PG8_WAIT_L(n) asm volatile("s_waitcnt lgkmcnt(" #n ")" ::: "memory")
; #define PG8_BAR __builtin_amdgcn_s_barrier()
; #define PG8_SCHED __builtin_amdgcn_sched_barrier(0)
; template <int MODE>
; __device__ __forceinline__ void gemm_phase(LAS unsigned char* lds, const Params& p, int l, int single) {
;     ...
;             PG8_LDB(B0, 0, 0); PG8_SCHED; PG8_LDA(At, 0, 0); PG8_STAGE(PG8_SA(1, 1), a1 + hstep, voffA);
;             PG8_WAIT_L(8); PG8_BAR; PG8_WAIT_L(0); PG8_MMA(0, 0, At, B0); PG8_BAR; PG8_SCHED;
;             PG8_LDB(B1, 0, 1); PG8_STAGE(PG8_SB(0, 0), b2, voffB);
;             PG8_BAR; PG8_WAIT_L(0); PG8_MMA(0, 1, At, B1); PG8_BAR;
;             PG8_LDA(At, 0, 1); PG8_STAGE(PG8_SA(0, 0), a2, voffA);
;             PG8_BAR; PG8_WAIT_L(0); PG8_MMA(1, 0, At, B0); PG8_BAR; PG8_SCHED;
;             PG8_STAGE(PG8_SB(0, 1), b2 + hstep, voffB);
;             PG8_WAIT_V(6); PG8_BAR; PG8_MMA(1, 1, At, B1); PG8_BAR;
.LBB0_376:
	s_add_u32 s20, s38, 0xfff80080
	s_addc_u32 s21, s39, -1
	s_add_i32 s23, 0, 0x10000
	v_add_u32_e32 v142, s23, v181
	ds_read_b128 v[130:133], v142
	ds_read_b128 v[174:177], v142 offset:1024
	ds_read_b128 v[184:187], v142 offset:2048
	ds_read_b128 v[188:191], v142 offset:3072
	s_cmp_eq_u32 s22, 28
	s_cselect_b32 vcc_hi, s79, s21
	s_cselect_b32 vcc_lo, s78, s20
	s_cselect_b32 s21, s19, s17
	s_cselect_b32 s20, s18, s15
	v_lshl_add_u64 v[142:143], s[38:39], 0, v[170:171]
	s_add_i32 m0, s90, 0xc000
	ds_read_b128 v[192:195], v161
	ds_read_b128 v[196:199], v161 offset:1024
	ds_read_b128 v[208:211], v161 offset:2048
	ds_read_b128 v[212:215], v161 offset:3072
	ds_read_b128 v[216:219], v161 offset:4096
	ds_read_b128 v[220:223], v161 offset:5120
	ds_read_b128 v[224:227], v161 offset:6144
	ds_read_b128 v[228:231], v161 offset:7168
	global_load_lds_dwordx4 v[142:143], off
	v_lshl_add_u64 v[142:143], s[38:39], 0, v[172:173]
	s_add_i32 m0, s90, 0xe000
	s_nop 0
	global_load_lds_dwordx4 v[142:143], off
	s_waitcnt lgkmcnt(8)
	s_barrier
	s_waitcnt lgkmcnt(0)
	s_waitcnt lgkmcnt(0)
	v_mfma_f32_16x16x32_bf16 v[126:129], v[130:133], v[192:195], v[126:129]
	v_mfma_f32_16x16x32_bf16 v[122:125], v[184:187], v[192:195], v[122:125]
	v_mfma_f32_16x16x32_bf16 v[118:121], v[130:133], v[208:211], v[118:121]
	v_mfma_f32_16x16x32_bf16 v[114:117], v[184:187], v[208:211], v[114:117]
	v_mfma_f32_16x16x32_bf16 v[110:113], v[130:133], v[216:219], v[110:113]
	v_mfma_f32_16x16x32_bf16 v[106:109], v[184:187], v[216:219], v[106:109]
	v_mfma_f32_16x16x32_bf16 v[102:105], v[130:133], v[224:227], v[102:105]
	v_mfma_f32_16x16x32_bf16 v[98:101], v[184:187], v[224:227], v[98:101]
	v_mfma_f32_16x16x32_bf16 v[126:129], v[174:177], v[196:199], v[126:129]
	v_mfma_f32_16x16x32_bf16 v[122:125], v[188:191], v[196:199], v[122:125]
	v_mfma_f32_16x16x32_bf16 v[118:121], v[174:177], v[212:215], v[118:121]
	v_mfma_f32_16x16x32_bf16 v[114:117], v[188:191], v[212:215], v[114:117]
	v_mfma_f32_16x16x32_bf16 v[110:113], v[174:177], v[220:223], v[110:113]
	v_mfma_f32_16x16x32_bf16 v[106:109], v[188:191], v[220:223], v[106:109]
	v_mfma_f32_16x16x32_bf16 v[102:105], v[174:177], v[228:231], v[102:105]
	v_mfma_f32_16x16x32_bf16 v[98:101], v[188:191], v[228:231], v[98:101]
	s_barrier
	s_add_i32 s6, 0, 0x14000
	v_add_u32_e32 v142, s6, v181
	s_add_i32 s23, s23, s76
	ds_read_b128 v[232:235], v142
	ds_read_b128 v[236:239], v142 offset:1024
	ds_read_b128 v[240:243], v142 offset:2048
	ds_read_b128 v[244:247], v142 offset:3072
	v_lshl_add_u64 v[142:143], s[20:21], 0, v[148:149]
	s_mov_b32 m0, s23
	v_lshl_add_u64 v[178:179], s[20:21], 0, v[152:153]
	global_load_lds_dwordx4 v[142:143], off
	s_add_i32 m0, s23, 0x2000
	s_nop 0
	global_load_lds_dwordx4 v[178:179], off
	s_barrier
	s_waitcnt lgkmcnt(0)
	s_waitcnt lgkmcnt(0)
	v_mfma_f32_16x16x32_bf16 v[62:65], v[232:235], v[192:195], v[62:65]
	v_mfma_f32_16x16x32_bf16 v[58:61], v[240:243], v[192:195], v[58:61]
	v_mfma_f32_16x16x32_bf16 v[54:57], v[232:235], v[208:211], v[54:57]
	v_mfma_f32_16x16x32_bf16 v[50:53], v[240:243], v[208:211], v[50:53]
	v_mfma_f32_16x16x32_bf16 v[46:49], v[232:235], v[216:219], v[46:49]
	v_mfma_f32_16x16x32_bf16 v[42:45], v[240:243], v[216:219], v[42:45]
	v_mfma_f32_16x16x32_bf16 v[38:41], v[232:235], v[224:227], v[38:41]
	v_mfma_f32_16x16x32_bf16 v[34:37], v[240:243], v[224:227], v[34:37]
	v_mfma_f32_16x16x32_bf16 v[62:65], v[236:239], v[196:199], v[62:65]
	v_mfma_f32_16x16x32_bf16 v[58:61], v[244:247], v[196:199], v[58:61]
	v_mfma_f32_16x16x32_bf16 v[54:57], v[236:239], v[212:215], v[54:57]
	v_mfma_f32_16x16x32_bf16 v[50:53], v[244:247], v[212:215], v[50:53]
	v_mfma_f32_16x16x32_bf16 v[46:49], v[236:239], v[220:223], v[46:49]
	v_mfma_f32_16x16x32_bf16 v[42:45], v[244:247], v[220:223], v[42:45]
	v_mfma_f32_16x16x32_bf16 v[38:41], v[236:239], v[228:231], v[38:41]
	v_mfma_f32_16x16x32_bf16 v[34:37], v[244:247], v[228:231], v[34:37]
	s_mov_b32 m0, s90
	v_lshl_add_u64 v[248:249], vcc, 0, v[146:147]
	s_barrier
	ds_read_b128 v[192:195], v161 offset:16384
	ds_read_b128 v[196:199], v161 offset:17408
	ds_read_b128 v[208:211], v161 offset:18432
	ds_read_b128 v[212:215], v161 offset:19456
	ds_read_b128 v[216:219], v161 offset:20480
	ds_read_b128 v[220:223], v161 offset:21504
	ds_read_b128 v[224:227], v161 offset:22528
	ds_read_b128 v[228:231], v161 offset:23552
	global_load_lds_dwordx4 v[248:249], off
	v_lshl_add_u64 v[250:251], vcc, 0, v[150:151]
	s_mov_b32 m0, s84
	s_nop 0
	global_load_lds_dwordx4 v[250:251], off
	s_barrier
	s_waitcnt lgkmcnt(0)
	s_waitcnt lgkmcnt(0)
	v_mfma_f32_16x16x32_bf16 v[94:97], v[130:133], v[192:195], v[94:97]
	v_mfma_f32_16x16x32_bf16 v[90:93], v[184:187], v[192:195], v[90:93]
	v_mfma_f32_16x16x32_bf16 v[86:89], v[130:133], v[208:211], v[86:89]
	v_mfma_f32_16x16x32_bf16 v[82:85], v[184:187], v[208:211], v[82:85]
	v_mfma_f32_16x16x32_bf16 v[78:81], v[130:133], v[216:219], v[78:81]
	v_mfma_f32_16x16x32_bf16 v[74:77], v[184:187], v[216:219], v[74:77]
	v_mfma_f32_16x16x32_bf16 v[70:73], v[130:133], v[224:227], v[70:73]
	v_mfma_f32_16x16x32_bf16 v[66:69], v[184:187], v[224:227], v[66:69]
	v_mfma_f32_16x16x32_bf16 v[94:97], v[174:177], v[196:199], v[94:97]
	v_mfma_f32_16x16x32_bf16 v[90:93], v[188:191], v[196:199], v[90:93]
	v_mfma_f32_16x16x32_bf16 v[86:89], v[174:177], v[212:215], v[86:89]
	v_mfma_f32_16x16x32_bf16 v[82:85], v[188:191], v[212:215], v[82:85]
	v_mfma_f32_16x16x32_bf16 v[78:81], v[174:177], v[220:223], v[78:81]
	v_mfma_f32_16x16x32_bf16 v[74:77], v[188:191], v[220:223], v[74:77]
	v_mfma_f32_16x16x32_bf16 v[70:73], v[174:177], v[228:231], v[70:73]
	v_mfma_f32_16x16x32_bf16 v[66:69], v[188:191], v[228:231], v[66:69]
	s_barrier
; #define PG8_STAGE(bufoff, gbase, voff) do { _Pragma("unroll") for (int _i = 0; _i < 2; ++_i) \
;         __builtin_amdgcn_global_load_lds((const unsigned*)((const char*)(gbase) + (voff)[_i]), (LAS unsigned*)(lds + (bufoff) + ldsw + _i * 8192), 16, 0, 0); } while (0)
; #define PG8_LDA(dst, b, h) do { _Pragma("unroll") for (int m = 0; m < 4; ++m) _Pragma("unroll") for (int k = 0; k < 2; ++k) dst[m][k] = *(const LAS bf16x8*)(lds + PG8_SA(b, h) + aoff + m * 2048 + k * 1024); } while (0)
; #define PG8_LDB(dst, b, h) do { _Pragma("unroll") for (int n = 0; n < 2; ++n) _Pragma("unroll") for (int k = 0; k < 2; ++k) dst[n][k] = *(const LAS bf16x8*)(lds + PG8_SB(b, h) + boff + n * 2048 + k * 1024); } while (0)
; #define PG8_MMA(ai, bj, At, Bt) do { __builtin_amdgcn_s_setprio(1); _Pragma("unroll") for (int m = 0; m < 4; ++m) _Pragma("unroll") for (int n = 0; n < 2; ++n) _Pragma("unroll") for (int k = 0; k < 2; ++k) \
;         acc[ai][bj][m][n] = __builtin_amdgcn_mfma_f32_16x16x32_bf16(Bt[n][k], At[m][k], acc[ai][bj][m][n], 0, 0, 0); __builtin_amdgcn_s_setprio(0); } while (0)
; #define PG8_WAIT_V(n) asm volatile("s_waitcnt vmcnt(" #n ")" ::: "memory")
; #define PG8_WAIT_L(n) asm volatile("s_waitcnt lgkmcnt(" #n ")" ::: "memory")
; #define PG8_BAR __builtin_amdgcn_s_barrier()
; #define PG8_SCHED __builtin_amdgcn_sched_barrier(0)
; template <int MODE>
; __device__ __forceinline__ void gemm_phase(LAS unsigned char* lds, const Params& p, int l, int single) {
;     ...
;             PG8_STAGE(PG8_SB(0, 1), b2 + hstep, voffB);
;             PG8_WAIT_V(6); PG8_BAR; PG8_MMA(1, 1, At, B1); PG8_BAR;
;             PG8_LDB(B0, 1, 0); PG8_SCHED; PG8_LDA(At, 1, 0); PG8_STAGE(PG8_SA(0, 1), a2 + hstep, voffA);
;             PG8_WAIT_L(8); PG8_BAR; PG8_WAIT_L(0); PG8_MMA(0, 0, At, B0); PG8_BAR; PG8_SCHED;
;             PG8_LDB(B1, 1, 1); PG8_STAGE(PG8_SB(1, 0), b3, voffB);
;             PG8_BAR; PG8_WAIT_L(0); PG8_MMA(0, 1, At, B1); PG8_BAR;
;             PG8_LDA(At, 1, 1); PG8_STAGE(PG8_SA(1, 0), a3, voffA);
	s_add_u32 s28, s20, 0x80000
	s_addc_u32 s29, s21, 0
	s_add_i32 s6, s6, s76
	v_lshl_add_u64 v[130:131], s[28:29], 0, v[148:149]
	s_mov_b32 m0, s6
	s_nop 0
	global_load_lds_dwordx4 v[130:131], off
	v_lshl_add_u64 v[130:131], s[28:29], 0, v[152:153]
	s_add_i32 m0, s6, 0x2000
	s_nop 0
	global_load_lds_dwordx4 v[130:131], off
	s_waitcnt vmcnt(6)
	s_barrier
	v_mfma_f32_16x16x32_bf16 v[30:33], v[232:235], v[192:195], v[30:33]
	v_mfma_f32_16x16x32_bf16 v[26:29], v[240:243], v[192:195], v[26:29]
	v_mfma_f32_16x16x32_bf16 v[22:25], v[232:235], v[208:211], v[22:25]
	v_mfma_f32_16x16x32_bf16 v[18:21], v[240:243], v[208:211], v[18:21]
	v_mfma_f32_16x16x32_bf16 v[14:17], v[232:235], v[216:219], v[14:17]
	v_mfma_f32_16x16x32_bf16 v[10:13], v[240:243], v[216:219], v[10:13]
	v_mfma_f32_16x16x32_bf16 v[6:9], v[232:235], v[224:227], v[6:9]
	v_mfma_f32_16x16x32_bf16 v[2:5], v[240:243], v[224:227], v[2:5]
	v_mfma_f32_16x16x32_bf16 v[30:33], v[236:239], v[196:199], v[30:33]
	v_mfma_f32_16x16x32_bf16 v[26:29], v[244:247], v[196:199], v[26:29]
	v_mfma_f32_16x16x32_bf16 v[22:25], v[236:239], v[212:215], v[22:25]
	v_mfma_f32_16x16x32_bf16 v[18:21], v[244:247], v[212:215], v[18:21]
	v_mfma_f32_16x16x32_bf16 v[14:17], v[236:239], v[220:223], v[14:17]
	v_mfma_f32_16x16x32_bf16 v[10:13], v[244:247], v[220:223], v[10:13]
	v_mfma_f32_16x16x32_bf16 v[6:9], v[236:239], v[228:231], v[6:9]
	v_mfma_f32_16x16x32_bf16 v[2:5], v[244:247], v[228:231], v[2:5]
	s_add_i32 s6, 0, 0x18000
	v_add_u32_e32 v155, s6, v181
	s_barrier
	ds_read_b128 v[130:133], v155
	ds_read_b128 v[174:177], v155 offset:1024
	ds_read_b128 v[184:187], v155 offset:2048
	ds_read_b128 v[188:191], v155 offset:3072
	s_add_u32 s28, vcc_lo, 0x80000
	s_addc_u32 s29, vcc_hi, 0
	s_mov_b32 m0, s85
	v_lshl_add_u64 v[232:233], s[28:29], 0, v[146:147]
	ds_read_b128 v[192:195], v161 offset:32768
	ds_read_b128 v[196:199], v161 offset:33792
	ds_read_b128 v[208:211], v161 offset:34816
	ds_read_b128 v[212:215], v161 offset:35840
	ds_read_b128 v[216:219], v161 offset:36864
	ds_read_b128 v[220:223], v161 offset:37888
	ds_read_b128 v[224:227], v161 offset:38912
	ds_read_b128 v[228:231], v161 offset:39936
	global_load_lds_dwordx4 v[232:233], off
	v_lshl_add_u64 v[232:233], s[28:29], 0, v[150:151]
	s_mov_b32 m0, s97
	s_nop 0
	global_load_lds_dwordx4 v[232:233], off
	s_waitcnt lgkmcnt(8)
	s_barrier
	s_waitcnt lgkmcnt(0)
	s_waitcnt lgkmcnt(0)
	v_mfma_f32_16x16x32_bf16 v[126:129], v[130:133], v[192:195], v[126:129]
	v_mfma_f32_16x16x32_bf16 v[122:125], v[184:187], v[192:195], v[122:125]
	v_mfma_f32_16x16x32_bf16 v[118:121], v[130:133], v[208:211], v[118:121]
	v_mfma_f32_16x16x32_bf16 v[114:117], v[184:187], v[208:211], v[114:117]
	v_mfma_f32_16x16x32_bf16 v[110:113], v[130:133], v[216:219], v[110:113]
	v_mfma_f32_16x16x32_bf16 v[106:109], v[184:187], v[216:219], v[106:109]
	v_mfma_f32_16x16x32_bf16 v[102:105], v[130:133], v[224:227], v[102:105]
	v_mfma_f32_16x16x32_bf16 v[98:101], v[184:187], v[224:227], v[98:101]
	v_mfma_f32_16x16x32_bf16 v[126:129], v[174:177], v[196:199], v[126:129]
	v_mfma_f32_16x16x32_bf16 v[122:125], v[188:191], v[196:199], v[122:125]
	v_mfma_f32_16x16x32_bf16 v[118:121], v[174:177], v[212:215], v[118:121]
	v_mfma_f32_16x16x32_bf16 v[114:117], v[188:191], v[212:215], v[114:117]
	v_mfma_f32_16x16x32_bf16 v[110:113], v[174:177], v[220:223], v[110:113]
	v_mfma_f32_16x16x32_bf16 v[106:109], v[188:191], v[220:223], v[106:109]
	v_mfma_f32_16x16x32_bf16 v[102:105], v[174:177], v[228:231], v[102:105]
	v_mfma_f32_16x16x32_bf16 v[98:101], v[188:191], v[228:231], v[98:101]
	s_barrier
	s_add_i32 s23, 0, 0x1c000
	s_add_i32 s6, s6, s76
	v_add_u32_e32 v155, s23, v181
	v_lshl_add_u64 v[142:143], v[142:143], 0, s[94:95]
	s_mov_b32 m0, s6
	ds_read_b128 v[232:235], v155
	ds_read_b128 v[236:239], v155 offset:1024
	ds_read_b128 v[240:243], v155 offset:2048
	ds_read_b128 v[244:247], v155 offset:3072
	global_load_lds_dwordx4 v[142:143], off
	v_lshl_add_u64 v[142:143], v[178:179], 0, s[94:95]
	s_add_i32 m0, s6, 0x2000
	s_nop 0
	global_load_lds_dwordx4 v[142:143], off
	s_barrier
; #define PG8_STAGE(bufoff, gbase, voff) do { _Pragma("unroll") for (int _i = 0; _i < 2; ++_i) \
;         __builtin_amdgcn_global_load_lds((const unsigned*)((const char*)(gbase) + (voff)[_i]), (LAS unsigned*)(lds + (bufoff) + ldsw + _i * 8192), 16, 0, 0); } while (0)
; #define PG8_LDA(dst, b, h) do { _Pragma("unroll") for (int m = 0; m < 4; ++m) _Pragma("unroll") for (int k = 0; k < 2; ++k) dst[m][k] = *(const LAS bf16x8*)(lds + PG8_SA(b, h) + aoff + m * 2048 + k * 1024); } while (0)
; #define PG8_MMA(ai, bj, At, Bt) do { __builtin_amdgcn_s_setprio(1); _Pragma("unroll") for (int m = 0; m < 4; ++m) _Pragma("unroll") for (int n = 0; n < 2; ++n) _Pragma("unroll") for (int k = 0; k < 2; ++k) \
;         acc[ai][bj][m][n] = __builtin_amdgcn_mfma_f32_16x16x32_bf16(Bt[n][k], At[m][k], acc[ai][bj][m][n], 0, 0, 0); __builtin_amdgcn_s_setprio(0); } while (0)
; #define PG8_WAIT_V(n) asm volatile("s_waitcnt vmcnt(" #n ")" ::: "memory")
; #define PG8_WAIT_L(n) asm volatile("s_waitcnt lgkmcnt(" #n ")" ::: "memory")
; #define PG8_BAR __builtin_amdgcn_s_barrier()
; #define PG8_SCHED __builtin_amdgcn_sched_barrier(0)
; template <int MODE>
; __device__ __forceinline__ void gemm_phase(LAS unsigned char* lds, const Params& p, int l, int single) {
;     ...
;             PG8_BAR; PG8_WAIT_L(0); PG8_MMA(0, 1, At, B1); PG8_BAR;
;             PG8_LDA(At, 1, 1); PG8_STAGE(PG8_SA(1, 0), a3, voffA);
;             PG8_BAR; PG8_WAIT_L(0); PG8_MMA(1, 0, At, B0); PG8_BAR; PG8_SCHED;
;             PG8_STAGE(PG8_SB(1, 1), b3 + hstep, voffB);
;             PG8_WAIT_V(6); PG8_BAR; PG8_MMA(1, 1, At, B1); PG8_BAR;
	s_waitcnt lgkmcnt(0)
	s_waitcnt lgkmcnt(0)
	v_mfma_f32_16x16x32_bf16 v[62:65], v[232:235], v[192:195], v[62:65]
	v_mfma_f32_16x16x32_bf16 v[58:61], v[240:243], v[192:195], v[58:61]
	v_mfma_f32_16x16x32_bf16 v[54:57], v[232:235], v[208:211], v[54:57]
	v_mfma_f32_16x16x32_bf16 v[50:53], v[240:243], v[208:211], v[50:53]
	v_mfma_f32_16x16x32_bf16 v[46:49], v[232:235], v[216:219], v[46:49]
	v_mfma_f32_16x16x32_bf16 v[42:45], v[240:243], v[216:219], v[42:45]
	v_mfma_f32_16x16x32_bf16 v[38:41], v[232:235], v[224:227], v[38:41]
	v_mfma_f32_16x16x32_bf16 v[34:37], v[240:243], v[224:227], v[34:37]
	v_mfma_f32_16x16x32_bf16 v[62:65], v[236:239], v[196:199], v[62:65]
	v_mfma_f32_16x16x32_bf16 v[58:61], v[244:247], v[196:199], v[58:61]
	v_mfma_f32_16x16x32_bf16 v[54:57], v[236:239], v[212:215], v[54:57]
	v_mfma_f32_16x16x32_bf16 v[50:53], v[244:247], v[212:215], v[50:53]
	v_mfma_f32_16x16x32_bf16 v[46:49], v[236:239], v[220:223], v[46:49]
	v_mfma_f32_16x16x32_bf16 v[42:45], v[244:247], v[220:223], v[42:45]
	v_mfma_f32_16x16x32_bf16 v[38:41], v[236:239], v[228:231], v[38:41]
	v_mfma_f32_16x16x32_bf16 v[34:37], v[244:247], v[228:231], v[34:37]
	s_mov_b32 m0, s33
	v_lshl_add_u64 v[142:143], v[248:249], 0, s[94:95]
	s_barrier
	ds_read_b128 v[192:195], v161 offset:49152
	ds_read_b128 v[196:199], v161 offset:50176
	ds_read_b128 v[208:211], v161 offset:51200
	ds_read_b128 v[212:215], v161 offset:52224
	ds_read_b128 v[216:219], v161 offset:53248
	ds_read_b128 v[220:223], v161 offset:54272
	ds_read_b128 v[224:227], v161 offset:55296
	ds_read_b128 v[228:231], v161 offset:56320
	global_load_lds_dwordx4 v[142:143], off
	v_lshl_add_u64 v[142:143], v[250:251], 0, s[94:95]
	s_mov_b32 m0, s24
	s_nop 0
	global_load_lds_dwordx4 v[142:143], off
	s_barrier
	s_waitcnt lgkmcnt(0)
	s_waitcnt lgkmcnt(0)
	v_mfma_f32_16x16x32_bf16 v[94:97], v[130:133], v[192:195], v[94:97]
	v_mfma_f32_16x16x32_bf16 v[90:93], v[184:187], v[192:195], v[90:93]
	v_mfma_f32_16x16x32_bf16 v[86:89], v[130:133], v[208:211], v[86:89]
	v_mfma_f32_16x16x32_bf16 v[82:85], v[184:187], v[208:211], v[82:85]
	v_mfma_f32_16x16x32_bf16 v[78:81], v[130:133], v[216:219], v[78:81]
	v_mfma_f32_16x16x32_bf16 v[74:77], v[184:187], v[216:219], v[74:77]
	v_mfma_f32_16x16x32_bf16 v[70:73], v[130:133], v[224:227], v[70:73]
	v_mfma_f32_16x16x32_bf16 v[66:69], v[184:187], v[224:227], v[66:69]
	v_mfma_f32_16x16x32_bf16 v[94:97], v[174:177], v[196:199], v[94:97]
	v_mfma_f32_16x16x32_bf16 v[90:93], v[188:191], v[196:199], v[90:93]
	v_mfma_f32_16x16x32_bf16 v[86:89], v[174:177], v[212:215], v[86:89]
	v_mfma_f32_16x16x32_bf16 v[82:85], v[188:191], v[212:215], v[82:85]
	v_mfma_f32_16x16x32_bf16 v[78:81], v[174:177], v[220:223], v[78:81]
	v_mfma_f32_16x16x32_bf16 v[74:77], v[188:191], v[220:223], v[74:77]
	v_mfma_f32_16x16x32_bf16 v[70:73], v[174:177], v[228:231], v[70:73]
	v_mfma_f32_16x16x32_bf16 v[66:69], v[188:191], v[228:231], v[66:69]
	s_barrier
	s_add_u32 s20, s20, 0x80080
	s_addc_u32 s21, s21, 0
	s_add_i32 s6, s23, s76
	v_lshl_add_u64 v[130:131], s[20:21], 0, v[148:149]
	s_mov_b32 m0, s6
	s_nop 0
	global_load_lds_dwordx4 v[130:131], off
	v_lshl_add_u64 v[130:131], s[20:21], 0, v[152:153]
	s_add_i32 m0, s6, 0x2000
	s_nop 0
	global_load_lds_dwordx4 v[130:131], off
	s_waitcnt vmcnt(6)
	s_barrier
	v_mfma_f32_16x16x32_bf16 v[30:33], v[232:235], v[192:195], v[30:33]
	v_mfma_f32_16x16x32_bf16 v[26:29], v[240:243], v[192:195], v[26:29]
	v_mfma_f32_16x16x32_bf16 v[22:25], v[232:235], v[208:211], v[22:25]
	v_mfma_f32_16x16x32_bf16 v[18:21], v[240:243], v[208:211], v[18:21]
	v_mfma_f32_16x16x32_bf16 v[14:17], v[232:235], v[216:219], v[14:17]
	v_mfma_f32_16x16x32_bf16 v[10:13], v[240:243], v[216:219], v[10:13]
	v_mfma_f32_16x16x32_bf16 v[6:9], v[232:235], v[224:227], v[6:9]
	v_mfma_f32_16x16x32_bf16 v[2:5], v[240:243], v[224:227], v[2:5]
	v_mfma_f32_16x16x32_bf16 v[30:33], v[236:239], v[196:199], v[30:33]
	v_mfma_f32_16x16x32_bf16 v[26:29], v[244:247], v[196:199], v[26:29]
	v_mfma_f32_16x16x32_bf16 v[22:25], v[236:239], v[212:215], v[22:25]
	v_mfma_f32_16x16x32_bf16 v[18:21], v[244:247], v[212:215], v[18:21]
	v_mfma_f32_16x16x32_bf16 v[14:17], v[236:239], v[220:223], v[14:17]
	v_mfma_f32_16x16x32_bf16 v[10:13], v[244:247], v[220:223], v[10:13]
	v_mfma_f32_16x16x32_bf16 v[6:9], v[236:239], v[228:231], v[6:9]
	v_mfma_f32_16x16x32_bf16 v[2:5], v[244:247], v[228:231], v[2:5]
	s_add_i32 s22, s22, 2
	s_add_u32 s38, s38, 0x100
	s_addc_u32 s39, s39, 0
	s_add_u32 s15, s15, 0x100
	s_addc_u32 s17, s17, 0
	s_cmp_gt_u32 s22, 29
	s_barrier
	s_cbranch_scc0 .LBB0_376
	s_and_b32 s15, s96, -4
	s_cmp_lt_i32 s15, 16
	s_cbranch_scc1 .LBB0_379
	s_cmp_lg_u32 s15, 16
	s_mov_b64 s[20:21], -1
	s_cselect_b64 s[22:23], -1, 0
	s_cbranch_execz .LBB0_380
	s_branch .LBB0_381

; #define PG8_STAGE(bufoff, gbase, voff) do { _Pragma("unroll") for (int _i = 0; _i < 2; ++_i) \
;         __builtin_amdgcn_global_load_lds((const unsigned*)((const char*)(gbase) + (voff)[_i]), (LAS unsigned*)(lds + (bufoff) + ldsw + _i * 8192), 16, 0, 0); } while (0)
; #define PG8_LDA(dst, b, h) do { _Pragma("unroll") for (int m = 0; m < 4; ++m) _Pragma("unroll") for (int k = 0; k < 2; ++k) dst[m][k] = *(const LAS bf16x8*)(lds + PG8_SA(b, h) + aoff + m * 2048 + k * 1024); } while (0)
; #define PG8_LDB(dst, b, h) do { _Pragma("unroll") for (int n = 0; n < 2; ++n) _Pragma("unroll") for (int k = 0; k < 2; ++k) dst[n][k] = *(const LAS bf16x8*)(lds + PG8_SB(b, h) + boff + n * 2048 + k * 1024); } while (0)
; #define PG8_MMA(ai, bj, At, Bt) do { __builtin_amdgcn_s_setprio(1); _Pragma("unroll") for (int m = 0; m < 4; ++m) _Pragma("unroll") for (int n = 0; n < 2; ++n) _Pragma("unroll") for (int k = 0; k < 2; ++k) \
;         acc[ai][bj][m][n] = __builtin_amdgcn_mfma_f32_16x16x32_bf16(Bt[n][k], At[m][k], acc[ai][bj][m][n], 0, 0, 0); __builtin_amdgcn_s_setprio(0); } while (0)
; #define PG8_WAIT_L(n) asm volatile("s_waitcnt lgkmcnt(" #n ")" ::: "memory")
; #define PG8_BAR __builtin_amdgcn_s_barrier()
; #define PG8_SCHED __builtin_amdgcn_sched_barrier(0)
; template <int MODE>
; __device__ __forceinline__ void gemm_phase(LAS unsigned char* lds, const Params& p, int l, int single) {
;     ...
;             PG8_LDB(B0, 0, 0); PG8_SCHED; PG8_LDA(At, 0, 0); PG8_STAGE(PG8_SA(1, 1), a1 + hstep, voffA);
;             PG8_WAIT_L(8); PG8_BAR; PG8_WAIT_L(0); PG8_MMA(0, 0, At, B0); PG8_BAR; PG8_SCHED;
;             PG8_LDB(B1, 0, 1); PG8_STAGE(PG8_SB(0, 0), b2, voffB);
;             PG8_BAR; PG8_WAIT_L(0); PG8_MMA(0, 1, At, B1); PG8_BAR;
;             PG8_LDA(At, 0, 1); PG8_STAGE(PG8_SA(0, 0), a2, voffA);
;             PG8_BAR; PG8_WAIT_L(0); PG8_MMA(1, 0, At, B0); PG8_BAR; PG8_SCHED;
.LBB0_643:
	s_add_u32 s20, s33, s38
	s_addc_u32 s21, s78, s39
	s_add_u32 s20, s20, 0x2d58c100
	s_addc_u32 s21, s21, 0
	s_add_u32 s90, s79, s38
	s_addc_u32 s93, s84, s39
	s_add_i32 s96, 0, 0x10000
	v_add_u32_e32 v142, s96, v155
	ds_read_b128 v[158:161], v142
	ds_read_b128 v[162:165], v142 offset:1024
	ds_read_b128 v[166:169], v142 offset:2048
	ds_read_b128 v[170:173], v142 offset:3072
	s_cmpk_eq_i32 s38, 0xf00
	s_cselect_b32 s41, s19, s21
	s_cselect_b32 s40, s18, s20
	s_cselect_b32 s21, s17, s93
	s_cselect_b32 s20, s16, s90
	v_lshl_add_u64 v[142:143], v[150:151], 0, s[38:39]
	s_add_i32 m0, s7, 0xc000
	ds_read_b128 v[174:177], v156
	ds_read_b128 v[178:181], v156 offset:1024
	ds_read_b128 v[182:185], v156 offset:2048
	ds_read_b128 v[186:189], v156 offset:3072
	ds_read_b128 v[190:193], v156 offset:4096
	ds_read_b128 v[194:197], v156 offset:5120
	ds_read_b128 v[208:211], v156 offset:6144
	ds_read_b128 v[212:215], v156 offset:7168
	global_load_lds_dwordx4 v[142:143], off
	v_lshl_add_u64 v[142:143], v[152:153], 0, s[38:39]
	s_add_i32 m0, s7, 0xe000
	s_nop 0
	global_load_lds_dwordx4 v[142:143], off
	s_waitcnt lgkmcnt(8)
	s_barrier
	s_waitcnt lgkmcnt(0)
	s_waitcnt lgkmcnt(0)
	v_mfma_f32_16x16x32_bf16 v[126:129], v[158:161], v[174:177], v[126:129]
	v_mfma_f32_16x16x32_bf16 v[122:125], v[166:169], v[174:177], v[122:125]
	v_mfma_f32_16x16x32_bf16 v[110:113], v[158:161], v[182:185], v[110:113]
	v_mfma_f32_16x16x32_bf16 v[106:109], v[166:169], v[182:185], v[106:109]
	v_mfma_f32_16x16x32_bf16 v[94:97], v[158:161], v[190:193], v[94:97]
	v_mfma_f32_16x16x32_bf16 v[90:93], v[166:169], v[190:193], v[90:93]
	v_mfma_f32_16x16x32_bf16 v[78:81], v[158:161], v[208:211], v[78:81]
	v_mfma_f32_16x16x32_bf16 v[74:77], v[166:169], v[208:211], v[74:77]
	v_mfma_f32_16x16x32_bf16 v[126:129], v[162:165], v[178:181], v[126:129]
	v_mfma_f32_16x16x32_bf16 v[122:125], v[170:173], v[178:181], v[122:125]
	v_mfma_f32_16x16x32_bf16 v[110:113], v[162:165], v[186:189], v[110:113]
	v_mfma_f32_16x16x32_bf16 v[106:109], v[170:173], v[186:189], v[106:109]
	v_mfma_f32_16x16x32_bf16 v[94:97], v[162:165], v[194:197], v[94:97]
	v_mfma_f32_16x16x32_bf16 v[90:93], v[170:173], v[194:197], v[90:93]
	v_mfma_f32_16x16x32_bf16 v[78:81], v[162:165], v[212:215], v[78:81]
	v_mfma_f32_16x16x32_bf16 v[74:77], v[170:173], v[212:215], v[74:77]
	s_barrier
	s_add_i32 s90, 0, 0x14000
	v_add_u32_e32 v142, s90, v155
	s_add_i32 s93, s96, s2
	ds_read_b128 v[216:219], v142
	ds_read_b128 v[220:223], v142 offset:1024
	ds_read_b128 v[224:227], v142 offset:2048
	ds_read_b128 v[228:231], v142 offset:3072
	v_lshl_add_u64 v[142:143], s[20:21], 0, v[0:1]
	s_mov_b32 m0, s93
	v_lshl_add_u64 v[198:199], s[20:21], 0, v[146:147]
	global_load_lds_dwordx4 v[142:143], off
	s_add_i32 m0, s93, 0x2000
	s_nop 0
	global_load_lds_dwordx4 v[198:199], off
	s_barrier
	s_waitcnt lgkmcnt(0)
	s_waitcnt lgkmcnt(0)
	v_mfma_f32_16x16x32_bf16 v[118:121], v[216:219], v[174:177], v[118:121]
	v_mfma_f32_16x16x32_bf16 v[114:117], v[224:227], v[174:177], v[114:117]
	v_mfma_f32_16x16x32_bf16 v[102:105], v[216:219], v[182:185], v[102:105]
	v_mfma_f32_16x16x32_bf16 v[98:101], v[224:227], v[182:185], v[98:101]
	v_mfma_f32_16x16x32_bf16 v[86:89], v[216:219], v[190:193], v[86:89]
	v_mfma_f32_16x16x32_bf16 v[82:85], v[224:227], v[190:193], v[82:85]
	v_mfma_f32_16x16x32_bf16 v[70:73], v[216:219], v[208:211], v[70:73]
	v_mfma_f32_16x16x32_bf16 v[66:69], v[224:227], v[208:211], v[66:69]
	v_mfma_f32_16x16x32_bf16 v[118:121], v[220:223], v[178:181], v[118:121]
	v_mfma_f32_16x16x32_bf16 v[114:117], v[228:231], v[178:181], v[114:117]
	v_mfma_f32_16x16x32_bf16 v[102:105], v[220:223], v[186:189], v[102:105]
	v_mfma_f32_16x16x32_bf16 v[98:101], v[228:231], v[186:189], v[98:101]
	v_mfma_f32_16x16x32_bf16 v[86:89], v[220:223], v[194:197], v[86:89]
	v_mfma_f32_16x16x32_bf16 v[82:85], v[228:231], v[194:197], v[82:85]
	v_mfma_f32_16x16x32_bf16 v[70:73], v[220:223], v[212:215], v[70:73]
	v_mfma_f32_16x16x32_bf16 v[66:69], v[228:231], v[212:215], v[66:69]
	s_mov_b32 m0, s7
	v_lshl_add_u64 v[232:233], s[40:41], 0, v[130:131]
	s_barrier
	ds_read_b128 v[174:177], v156 offset:16384
	ds_read_b128 v[178:181], v156 offset:17408
	ds_read_b128 v[182:185], v156 offset:18432
	ds_read_b128 v[186:189], v156 offset:19456
	ds_read_b128 v[190:193], v156 offset:20480
	ds_read_b128 v[194:197], v156 offset:21504
	ds_read_b128 v[208:211], v156 offset:22528
	ds_read_b128 v[212:215], v156 offset:23552
	global_load_lds_dwordx4 v[232:233], off
	v_lshl_add_u64 v[234:235], s[40:41], 0, v[132:133]
	s_mov_b32 m0, s10
	s_nop 0
	global_load_lds_dwordx4 v[234:235], off
	s_barrier
	s_waitcnt lgkmcnt(0)
	s_waitcnt lgkmcnt(0)
	v_mfma_f32_16x16x32_bf16 v[62:65], v[158:161], v[174:177], v[62:65]
	v_mfma_f32_16x16x32_bf16 v[58:61], v[166:169], v[174:177], v[58:61]
	v_mfma_f32_16x16x32_bf16 v[46:49], v[158:161], v[182:185], v[46:49]
	v_mfma_f32_16x16x32_bf16 v[42:45], v[166:169], v[182:185], v[42:45]
	v_mfma_f32_16x16x32_bf16 v[30:33], v[158:161], v[190:193], v[30:33]
	v_mfma_f32_16x16x32_bf16 v[26:29], v[166:169], v[190:193], v[26:29]
	v_mfma_f32_16x16x32_bf16 v[14:17], v[158:161], v[208:211], v[14:17]
	v_mfma_f32_16x16x32_bf16 v[10:13], v[166:169], v[208:211], v[10:13]
	v_mfma_f32_16x16x32_bf16 v[62:65], v[162:165], v[178:181], v[62:65]
	v_mfma_f32_16x16x32_bf16 v[58:61], v[170:173], v[178:181], v[58:61]
	v_mfma_f32_16x16x32_bf16 v[46:49], v[162:165], v[186:189], v[46:49]
	v_mfma_f32_16x16x32_bf16 v[42:45], v[170:173], v[186:189], v[42:45]
	v_mfma_f32_16x16x32_bf16 v[30:33], v[162:165], v[194:197], v[30:33]
	v_mfma_f32_16x16x32_bf16 v[26:29], v[170:173], v[194:197], v[26:29]
	v_mfma_f32_16x16x32_bf16 v[14:17], v[162:165], v[212:215], v[14:17]
	v_mfma_f32_16x16x32_bf16 v[10:13], v[170:173], v[212:215], v[10:13]
	s_barrier
; #define PG8_STAGE(bufoff, gbase, voff) do { _Pragma("unroll") for (int _i = 0; _i < 2; ++_i) \
;         __builtin_amdgcn_global_load_lds((const unsigned*)((const char*)(gbase) + (voff)[_i]), (LAS unsigned*)(lds + (bufoff) + ldsw + _i * 8192), 16, 0, 0); } while (0)
; #define PG8_LDA(dst, b, h) do { _Pragma("unroll") for (int m = 0; m < 4; ++m) _Pragma("unroll") for (int k = 0; k < 2; ++k) dst[m][k] = *(const LAS bf16x8*)(lds + PG8_SA(b, h) + aoff + m * 2048 + k * 1024); } while (0)
; #define PG8_LDB(dst, b, h) do { _Pragma("unroll") for (int n = 0; n < 2; ++n) _Pragma("unroll") for (int k = 0; k < 2; ++k) dst[n][k] = *(const LAS bf16x8*)(lds + PG8_SB(b, h) + boff + n * 2048 + k * 1024); } while (0)
; #define PG8_MMA(ai, bj, At, Bt) do { __builtin_amdgcn_s_setprio(1); _Pragma("unroll") for (int m = 0; m < 4; ++m) _Pragma("unroll") for (int n = 0; n < 2; ++n) _Pragma("unroll") for (int k = 0; k < 2; ++k) \
;         acc[ai][bj][m][n] = __builtin_amdgcn_mfma_f32_16x16x32_bf16(Bt[n][k], At[m][k], acc[ai][bj][m][n], 0, 0, 0); __builtin_amdgcn_s_setprio(0); } while (0)
; #define PG8_WAIT_V(n) asm volatile("s_waitcnt vmcnt(" #n ")" ::: "memory")
; #define PG8_WAIT_L(n) asm volatile("s_waitcnt lgkmcnt(" #n ")" ::: "memory")
; #define PG8_BAR __builtin_amdgcn_s_barrier()
; #define PG8_SCHED __builtin_amdgcn_sched_barrier(0)
; template <int MODE>
; __device__ __forceinline__ void gemm_phase(LAS unsigned char* lds, const Params& p, int l, int single) {
;     ...
;             PG8_STAGE(PG8_SB(0, 1), b2 + hstep, voffB);
;             PG8_WAIT_V(6); PG8_BAR; PG8_MMA(1, 1, At, B1); PG8_BAR;
;             PG8_LDB(B0, 1, 0); PG8_SCHED; PG8_LDA(At, 1, 0); PG8_STAGE(PG8_SA(0, 1), a2 + hstep, voffA);
;             PG8_WAIT_L(8); PG8_BAR; PG8_WAIT_L(0); PG8_MMA(0, 0, At, B0); PG8_BAR; PG8_SCHED;
;             PG8_LDB(B1, 1, 1); PG8_STAGE(PG8_SB(1, 0), b3, voffB);
;             PG8_BAR; PG8_WAIT_L(0); PG8_MMA(0, 1, At, B1); PG8_BAR;
;             PG8_LDA(At, 1, 1); PG8_STAGE(PG8_SA(1, 0), a3, voffA);
	s_add_u32 s96, s20, 0x80000
	s_addc_u32 s97, s21, 0
	s_add_i32 s90, s90, s2
	v_lshl_add_u64 v[158:159], s[96:97], 0, v[0:1]
	s_mov_b32 m0, s90
	s_nop 0
	global_load_lds_dwordx4 v[158:159], off
	v_lshl_add_u64 v[158:159], s[96:97], 0, v[146:147]
	s_add_i32 m0, s90, 0x2000
	s_nop 0
	global_load_lds_dwordx4 v[158:159], off
	s_waitcnt vmcnt(6)
	s_barrier
	v_mfma_f32_16x16x32_bf16 v[54:57], v[216:219], v[174:177], v[54:57]
	v_mfma_f32_16x16x32_bf16 v[50:53], v[224:227], v[174:177], v[50:53]
	v_mfma_f32_16x16x32_bf16 v[38:41], v[216:219], v[182:185], v[38:41]
	v_mfma_f32_16x16x32_bf16 v[34:37], v[224:227], v[182:185], v[34:37]
	v_mfma_f32_16x16x32_bf16 v[22:25], v[216:219], v[190:193], v[22:25]
	v_mfma_f32_16x16x32_bf16 v[18:21], v[224:227], v[190:193], v[18:21]
	v_mfma_f32_16x16x32_bf16 v[6:9], v[216:219], v[208:211], v[6:9]
	v_mfma_f32_16x16x32_bf16 v[2:5], v[224:227], v[208:211], v[2:5]
	v_mfma_f32_16x16x32_bf16 v[54:57], v[220:223], v[178:181], v[54:57]
	v_mfma_f32_16x16x32_bf16 v[50:53], v[228:231], v[178:181], v[50:53]
	v_mfma_f32_16x16x32_bf16 v[38:41], v[220:223], v[186:189], v[38:41]
	v_mfma_f32_16x16x32_bf16 v[34:37], v[228:231], v[186:189], v[34:37]
	v_mfma_f32_16x16x32_bf16 v[22:25], v[220:223], v[194:197], v[22:25]
	v_mfma_f32_16x16x32_bf16 v[18:21], v[228:231], v[194:197], v[18:21]
	v_mfma_f32_16x16x32_bf16 v[6:9], v[220:223], v[212:215], v[6:9]
	v_mfma_f32_16x16x32_bf16 v[2:5], v[228:231], v[212:215], v[2:5]
	s_add_i32 s90, 0, 0x18000
	v_add_u32_e32 v157, s90, v155
	s_barrier
	ds_read_b128 v[158:161], v157
	ds_read_b128 v[162:165], v157 offset:1024
	ds_read_b128 v[166:169], v157 offset:2048
	ds_read_b128 v[170:173], v157 offset:3072
	s_add_u32 s40, s40, 0x80000
	s_addc_u32 s41, s41, 0
	s_mov_b32 m0, s24
	v_lshl_add_u64 v[216:217], s[40:41], 0, v[130:131]
	ds_read_b128 v[174:177], v156 offset:32768
	ds_read_b128 v[178:181], v156 offset:33792
	ds_read_b128 v[182:185], v156 offset:34816
	ds_read_b128 v[186:189], v156 offset:35840
	ds_read_b128 v[190:193], v156 offset:36864
	ds_read_b128 v[194:197], v156 offset:37888
	ds_read_b128 v[208:211], v156 offset:38912
	ds_read_b128 v[212:215], v156 offset:39936
	global_load_lds_dwordx4 v[216:217], off
	v_lshl_add_u64 v[216:217], s[40:41], 0, v[132:133]
	s_mov_b32 m0, s25
	s_nop 0
	global_load_lds_dwordx4 v[216:217], off
	s_waitcnt lgkmcnt(8)
	s_barrier
	s_waitcnt lgkmcnt(0)
	s_waitcnt lgkmcnt(0)
	v_mfma_f32_16x16x32_bf16 v[126:129], v[158:161], v[174:177], v[126:129]
	v_mfma_f32_16x16x32_bf16 v[122:125], v[166:169], v[174:177], v[122:125]
	v_mfma_f32_16x16x32_bf16 v[110:113], v[158:161], v[182:185], v[110:113]
	v_mfma_f32_16x16x32_bf16 v[106:109], v[166:169], v[182:185], v[106:109]
	v_mfma_f32_16x16x32_bf16 v[94:97], v[158:161], v[190:193], v[94:97]
	v_mfma_f32_16x16x32_bf16 v[90:93], v[166:169], v[190:193], v[90:93]
	v_mfma_f32_16x16x32_bf16 v[78:81], v[158:161], v[208:211], v[78:81]
	v_mfma_f32_16x16x32_bf16 v[74:77], v[166:169], v[208:211], v[74:77]
	v_mfma_f32_16x16x32_bf16 v[126:129], v[162:165], v[178:181], v[126:129]
	v_mfma_f32_16x16x32_bf16 v[122:125], v[170:173], v[178:181], v[122:125]
	v_mfma_f32_16x16x32_bf16 v[110:113], v[162:165], v[186:189], v[110:113]
	v_mfma_f32_16x16x32_bf16 v[106:109], v[170:173], v[186:189], v[106:109]
	v_mfma_f32_16x16x32_bf16 v[94:97], v[162:165], v[194:197], v[94:97]
	v_mfma_f32_16x16x32_bf16 v[90:93], v[170:173], v[194:197], v[90:93]
	v_mfma_f32_16x16x32_bf16 v[78:81], v[162:165], v[212:215], v[78:81]
	v_mfma_f32_16x16x32_bf16 v[74:77], v[170:173], v[212:215], v[74:77]
	s_barrier
	s_add_i32 s40, 0, 0x1c000
	s_add_i32 s41, s90, s2
	v_add_u32_e32 v157, s40, v155
	v_lshl_add_u64 v[142:143], v[142:143], 0, s[94:95]
	s_mov_b32 m0, s41
	ds_read_b128 v[216:219], v157
	ds_read_b128 v[220:223], v157 offset:1024
	ds_read_b128 v[224:227], v157 offset:2048
	ds_read_b128 v[228:231], v157 offset:3072
	global_load_lds_dwordx4 v[142:143], off
	v_lshl_add_u64 v[142:143], v[198:199], 0, s[94:95]
	s_add_i32 m0, s41, 0x2000
	s_nop 0
	global_load_lds_dwordx4 v[142:143], off
	s_barrier
	s_waitcnt lgkmcnt(0)
	s_waitcnt lgkmcnt(0)
	v_mfma_f32_16x16x32_bf16 v[118:121], v[216:219], v[174:177], v[118:121]
	v_mfma_f32_16x16x32_bf16 v[114:117], v[224:227], v[174:177], v[114:117]
	v_mfma_f32_16x16x32_bf16 v[102:105], v[216:219], v[182:185], v[102:105]
	v_mfma_f32_16x16x32_bf16 v[98:101], v[224:227], v[182:185], v[98:101]
	v_mfma_f32_16x16x32_bf16 v[86:89], v[216:219], v[190:193], v[86:89]
	v_mfma_f32_16x16x32_bf16 v[82:85], v[224:227], v[190:193], v[82:85]
	v_mfma_f32_16x16x32_bf16 v[70:73], v[216:219], v[208:211], v[70:73]
	v_mfma_f32_16x16x32_bf16 v[66:69], v[224:227], v[208:211], v[66:69]
	v_mfma_f32_16x16x32_bf16 v[118:121], v[220:223], v[178:181], v[118:121]
	v_mfma_f32_16x16x32_bf16 v[114:117], v[228:231], v[178:181], v[114:117]
	v_mfma_f32_16x16x32_bf16 v[102:105], v[220:223], v[186:189], v[102:105]
	v_mfma_f32_16x16x32_bf16 v[98:101], v[228:231], v[186:189], v[98:101]
	v_mfma_f32_16x16x32_bf16 v[86:89], v[220:223], v[194:197], v[86:89]
	v_mfma_f32_16x16x32_bf16 v[82:85], v[228:231], v[194:197], v[82:85]
	v_mfma_f32_16x16x32_bf16 v[70:73], v[220:223], v[212:215], v[70:73]
	v_mfma_f32_16x16x32_bf16 v[66:69], v[228:231], v[212:215], v[66:69]
	s_mov_b32 m0, s28
	v_lshl_add_u64 v[142:143], v[232:233], 0, s[94:95]
	s_barrier
	ds_read_b128 v[174:177], v156 offset:49152
	ds_read_b128 v[178:181], v156 offset:50176
	ds_read_b128 v[182:185], v156 offset:51200
	ds_read_b128 v[186:189], v156 offset:52224
	ds_read_b128 v[190:193], v156 offset:53248
	ds_read_b128 v[194:197], v156 offset:54272
	ds_read_b128 v[208:211], v156 offset:55296
	ds_read_b128 v[212:215], v156 offset:56320
	global_load_lds_dwordx4 v[142:143], off
	v_lshl_add_u64 v[142:143], v[234:235], 0, s[94:95]
	s_mov_b32 m0, s29
	s_nop 0
	global_load_lds_dwordx4 v[142:143], off
	s_barrier
; #define PG8_STAGE(bufoff, gbase, voff) do { _Pragma("unroll") for (int _i = 0; _i < 2; ++_i) \
;         __builtin_amdgcn_global_load_lds((const unsigned*)((const char*)(gbase) + (voff)[_i]), (LAS unsigned*)(lds + (bufoff) + ldsw + _i * 8192), 16, 0, 0); } while (0)
; #define PG8_MMA(ai, bj, At, Bt) do { __builtin_amdgcn_s_setprio(1); _Pragma("unroll") for (int m = 0; m < 4; ++m) _Pragma("unroll") for (int n = 0; n < 2; ++n) _Pragma("unroll") for (int k = 0; k < 2; ++k) \
;         acc[ai][bj][m][n] = __builtin_amdgcn_mfma_f32_16x16x32_bf16(Bt[n][k], At[m][k], acc[ai][bj][m][n], 0, 0, 0); __builtin_amdgcn_s_setprio(0); } while (0)
; #define PG8_WAIT_V(n) asm volatile("s_waitcnt vmcnt(" #n ")" ::: "memory")
; #define PG8_WAIT_L(n) asm volatile("s_waitcnt lgkmcnt(" #n ")" ::: "memory")
; #define PG8_BAR __builtin_amdgcn_s_barrier()
; #define PG8_SCHED __builtin_amdgcn_sched_barrier(0)
; template <int MODE>
; __device__ __forceinline__ void gemm_phase(LAS unsigned char* lds, const Params& p, int l, int single) {
;     ...
;             PG8_BAR; PG8_WAIT_L(0); PG8_MMA(1, 0, At, B0); PG8_BAR; PG8_SCHED;
;             PG8_STAGE(PG8_SB(1, 1), b3 + hstep, voffB);
;             PG8_WAIT_V(6); PG8_BAR; PG8_MMA(1, 1, At, B1); PG8_BAR;
;         }
	s_waitcnt lgkmcnt(0)
	s_waitcnt lgkmcnt(0)
	v_mfma_f32_16x16x32_bf16 v[62:65], v[158:161], v[174:177], v[62:65]
	v_mfma_f32_16x16x32_bf16 v[58:61], v[166:169], v[174:177], v[58:61]
	v_mfma_f32_16x16x32_bf16 v[46:49], v[158:161], v[182:185], v[46:49]
	v_mfma_f32_16x16x32_bf16 v[42:45], v[166:169], v[182:185], v[42:45]
	v_mfma_f32_16x16x32_bf16 v[30:33], v[158:161], v[190:193], v[30:33]
	v_mfma_f32_16x16x32_bf16 v[26:29], v[166:169], v[190:193], v[26:29]
	v_mfma_f32_16x16x32_bf16 v[14:17], v[158:161], v[208:211], v[14:17]
	v_mfma_f32_16x16x32_bf16 v[10:13], v[166:169], v[208:211], v[10:13]
	v_mfma_f32_16x16x32_bf16 v[62:65], v[162:165], v[178:181], v[62:65]
	v_mfma_f32_16x16x32_bf16 v[58:61], v[170:173], v[178:181], v[58:61]
	v_mfma_f32_16x16x32_bf16 v[46:49], v[162:165], v[186:189], v[46:49]
	v_mfma_f32_16x16x32_bf16 v[42:45], v[170:173], v[186:189], v[42:45]
	v_mfma_f32_16x16x32_bf16 v[30:33], v[162:165], v[194:197], v[30:33]
	v_mfma_f32_16x16x32_bf16 v[26:29], v[170:173], v[194:197], v[26:29]
	v_mfma_f32_16x16x32_bf16 v[14:17], v[162:165], v[212:215], v[14:17]
	v_mfma_f32_16x16x32_bf16 v[10:13], v[170:173], v[212:215], v[10:13]
	s_barrier
	s_add_u32 s20, s20, 0x80080
	s_addc_u32 s21, s21, 0
	s_add_i32 s40, s40, s2
	v_lshl_add_u64 v[142:143], s[20:21], 0, v[0:1]
	s_mov_b32 m0, s40
	s_nop 0
	global_load_lds_dwordx4 v[142:143], off
	v_lshl_add_u64 v[142:143], s[20:21], 0, v[146:147]
	s_add_i32 m0, s40, 0x2000
	s_nop 0
	global_load_lds_dwordx4 v[142:143], off
	s_waitcnt vmcnt(6)
	s_barrier
	v_mfma_f32_16x16x32_bf16 v[54:57], v[216:219], v[174:177], v[54:57]
	v_mfma_f32_16x16x32_bf16 v[50:53], v[224:227], v[174:177], v[50:53]
	v_mfma_f32_16x16x32_bf16 v[38:41], v[216:219], v[182:185], v[38:41]
	v_mfma_f32_16x16x32_bf16 v[34:37], v[224:227], v[182:185], v[34:37]
	v_mfma_f32_16x16x32_bf16 v[22:25], v[216:219], v[190:193], v[22:25]
	v_mfma_f32_16x16x32_bf16 v[18:21], v[224:227], v[190:193], v[18:21]
	v_mfma_f32_16x16x32_bf16 v[6:9], v[216:219], v[208:211], v[6:9]
	v_mfma_f32_16x16x32_bf16 v[2:5], v[224:227], v[208:211], v[2:5]
	v_mfma_f32_16x16x32_bf16 v[54:57], v[220:223], v[178:181], v[54:57]
	v_mfma_f32_16x16x32_bf16 v[50:53], v[228:231], v[178:181], v[50:53]
	v_mfma_f32_16x16x32_bf16 v[38:41], v[220:223], v[186:189], v[38:41]
	v_mfma_f32_16x16x32_bf16 v[34:37], v[228:231], v[186:189], v[34:37]
	v_mfma_f32_16x16x32_bf16 v[22:25], v[220:223], v[194:197], v[22:25]
	v_mfma_f32_16x16x32_bf16 v[18:21], v[228:231], v[194:197], v[18:21]
	v_mfma_f32_16x16x32_bf16 v[6:9], v[220:223], v[212:215], v[6:9]
	v_mfma_f32_16x16x32_bf16 v[2:5], v[228:231], v[212:215], v[2:5]
	s_add_i32 s85, s85, 2
	s_add_u32 s38, s38, 0x100
	s_addc_u32 s39, s39, 0
	s_cmp_gt_u32 s85, 29
	s_barrier
	s_cbranch_scc0 .LBB0_643
; __device__ __forceinline__ unsigned cvt_pk_bf16(float lo, float hi) { unsigned r; asm("v_cvt_pk_bf16_f32 %0, %1, %2" : "=v"(r) : "v"(lo), "v"(hi)); return r; }
; __device__ __forceinline__ float bflo(unsigned w) { return __uint_as_float(w << 16); }
; __device__ __forceinline__ float bfhi(unsigned w) { return __uint_as_float(w & 0xffff0000u); }
; #define WT_STORE16(ptr, val) __builtin_amdgcn_raw_buffer_store_b128((val), wsr, (int)((const char*)(ptr) - (const char*)ws), 0, 16)
; template <int MODE>
; __device__ __forceinline__ void gemm_epilogue(const Params& p, int l, const f32x4 (&acc)[2][2][4][2], const Unit& u, int wr, int wc, int fr, int fq, const LAS float* rl, int pm0) {
;     ...
;         u16* xb = (u16*)(ws + WS_XB);
;         u64* ssn = (u64*)(ws + WS_SUMSQ) + (size_t)(l + 1) * T;
; #pragma unroll
;         for (int ai = 0; ai < 2; ++ai)
; #pragma unroll
;             for (int m = 0; m < 4; ++m) {
;                 const int tok = u.pm * 256 + 128 * ai + 64 * wr + 16 * m + fr;
;                 float part = 0.f;
; #pragma unroll
;                 for (int bj = 0; bj < 2; ++bj) {
;                     const size_t idx = (size_t)tok * 2048 + u.pn * 256 + 128 * bj + 32 * wc + 8 * fq;
;                     const u32x4 xw = *(const u32x4*)(xb + idx);
;                     f32x4 y0 = (f32x4){bflo(xw.x), bfhi(xw.x), bflo(xw.y), bfhi(xw.y)}, y1 = (f32x4){bflo(xw.z), bfhi(xw.z), bflo(xw.w), bfhi(xw.w)};
;                     y0 += acc[ai][bj][m][0]; y1 += acc[ai][bj][m][1];
;                     part += y0[0] * y0[0] + y0[1] * y0[1] + y0[2] * y0[2] + y0[3] * y0[3] + y1[0] * y1[0] + y1[1] * y1[1] + y1[2] * y1[2] + y1[3] * y1[3];
;                     u32x4 w; w.x = cvt_pk_bf16(y0[0], y0[1]); w.y = cvt_pk_bf16(y0[2], y0[3]); w.z = cvt_pk_bf16(y1[0], y1[1]); w.w = cvt_pk_bf16(y1[2], y1[3]);
;                     WT_STORE16(xb + idx, w);
;                 }
;                 part += __shfl_xor(part, 16); part += __shfl_xor(part, 32);
;                 if (fq == 0) atomicAdd(ssn + tok, (u64)(part * SS_SCALE));
;             }
	s_add_i32 s0, s0, 1
	s_mul_hi_i32 s2, s0, 0x21000
	s_mul_i32 s0, s0, 0x21000
	s_add_u32 s16, s80, s0
	s_addc_u32 s17, s81, s2
	s_lshl_b32 s2, s1, 8
	s_lshl_b32 s0, s1, 9
	s_add_u32 s0, s52, s0
	s_addc_u32 s1, s53, 0
	s_lshl_b32 s7, s11, 1
	v_lshl_add_u32 v130, s76, 8, v149
	s_add_u32 s0, s0, s7
	s_addc_u32 s1, s1, 0
	v_mov_b32_e32 v149, v1
	v_ashrrev_i32_e32 v131, 31, v130
	v_lshl_add_u64 v[132:133], s[0:1], 0, v[148:149]
	v_mov_b32_e32 v162, v130
	v_ashrrev_i32_e32 v163, 31, v162
	v_lshlrev_b64 v[162:163], 12, v[162:163]
	v_lshl_add_u64 v[162:163], v[132:133], 0, v[162:163]
	global_load_dwordx4 v[158:161], v[162:163], off
	global_load_dwordx4 v[162:165], v[162:163], off offset:256
	v_add_u32_e32 v170, 0x10, v130
	v_ashrrev_i32_e32 v171, 31, v170
	v_lshlrev_b64 v[170:171], 12, v[170:171]
	v_lshl_add_u64 v[170:171], v[132:133], 0, v[170:171]
	global_load_dwordx4 v[166:169], v[170:171], off
	global_load_dwordx4 v[170:173], v[170:171], off offset:256
	v_add_u32_e32 v178, 0x20, v130
	v_ashrrev_i32_e32 v179, 31, v178
	v_lshlrev_b64 v[178:179], 12, v[178:179]
	v_lshl_add_u64 v[178:179], v[132:133], 0, v[178:179]
	global_load_dwordx4 v[174:177], v[178:179], off
	global_load_dwordx4 v[178:181], v[178:179], off offset:256
	v_add_u32_e32 v186, 0x30, v130
	v_ashrrev_i32_e32 v187, 31, v186
	v_lshlrev_b64 v[186:187], 12, v[186:187]
	v_lshl_add_u64 v[186:187], v[132:133], 0, v[186:187]
	global_load_dwordx4 v[182:185], v[186:187], off
	global_load_dwordx4 v[186:189], v[186:187], off offset:256
	v_add_u32_e32 v194, 0x80, v130
	v_ashrrev_i32_e32 v195, 31, v194
	v_lshlrev_b64 v[194:195], 12, v[194:195]
	v_lshl_add_u64 v[194:195], v[132:133], 0, v[194:195]
	global_load_dwordx4 v[190:193], v[194:195], off
	global_load_dwordx4 v[194:197], v[194:195], off offset:256
	v_add_u32_e32 v212, 0x90, v130
	v_ashrrev_i32_e32 v213, 31, v212
	v_lshlrev_b64 v[212:213], 12, v[212:213]
	v_lshl_add_u64 v[212:213], v[132:133], 0, v[212:213]
	global_load_dwordx4 v[208:211], v[212:213], off
	global_load_dwordx4 v[212:215], v[212:213], off offset:256
	v_add_u32_e32 v220, 0xa0, v130
	v_ashrrev_i32_e32 v221, 31, v220
	v_lshlrev_b64 v[220:221], 12, v[220:221]
	v_lshl_add_u64 v[220:221], v[132:133], 0, v[220:221]
	global_load_dwordx4 v[216:219], v[220:221], off
	global_load_dwordx4 v[220:223], v[220:221], off offset:256
	v_add_u32_e32 v228, 0xb0, v130
	v_ashrrev_i32_e32 v229, 31, v228
	v_lshlrev_b64 v[228:229], 12, v[228:229]
	v_lshl_add_u64 v[228:229], v[132:133], 0, v[228:229]
	global_load_dwordx4 v[224:227], v[228:229], off
	global_load_dwordx4 v[228:231], v[228:229], off offset:256
	v_lshlrev_b64 v[142:143], 12, v[130:131]
	v_lshl_add_u64 v[152:153], v[132:133], 0, v[142:143]
	v_lshl_or_b32 v0, v154, 3, s2
	v_or_b32_e32 v0, s11, v0
	v_add_u32_e32 v146, 0x10800000, v142
	v_lshlrev_b32_e32 v0, 1, v0
	v_or_b32_e32 v147, v146, v0
	v_cmp_eq_u32_e32 vcc, 0, v154
	s_waitcnt vmcnt(15)
	v_mov_b32_e32 v148, v158
	v_mov_b32_e32 v149, v159
	v_mov_b32_e32 v150, v160
	v_mov_b32_e32 v151, v161
	v_lshlrev_b32_e32 v142, 16, v148
	v_and_b32_e32 v143, 0xffff0000, v148
	v_lshlrev_b32_e32 v148, 16, v149
	v_and_b32_e32 v149, 0xffff0000, v149
	v_lshlrev_b32_e32 v156, 16, v150
	v_and_b32_e32 v157, 0xffff0000, v150
	v_lshlrev_b32_e32 v150, 16, v151
	v_and_b32_e32 v151, 0xffff0000, v151
	v_pk_add_f32 v[128:129], v[128:129], v[148:149]
	v_pk_add_f32 v[142:143], v[126:127], v[142:143]
	v_pk_add_f32 v[124:125], v[124:125], v[150:151]
	v_pk_add_f32 v[122:123], v[122:123], v[156:157]
	v_cvt_pk_bf16_f32 v148, v142, v143
	v_cvt_pk_bf16_f32 v149, v128, v129
	v_cvt_pk_bf16_f32 v151, v124, v125
	v_and_b32_e32 v127, 64, v205
	v_cvt_pk_bf16_f32 v150, v122, v123
	buffer_store_dwordx4 v[148:151], v147, s[60:63], 0 offen
	v_xor_b32_e32 v126, 16, v205
	v_add_u32_e32 v127, 64, v127
	v_xor_b32_e32 v147, 32, v205
	v_cmp_lt_i32_e64 s[0:1], v126, v127
	s_nop 1
	v_cndmask_b32_e64 v126, v205, v126, s[0:1]
	v_cmp_lt_i32_e64 s[0:1], v147, v127
	v_lshlrev_b32_e32 v126, 2, v126
	s_nop 0
	v_cndmask_b32_e64 v127, v205, v147, s[0:1]
	v_mul_f32_e32 v147, v143, v143
	v_fmac_f32_e32 v147, v142, v142
	v_fmac_f32_e32 v147, v128, v128
	v_fmac_f32_e32 v147, v129, v129
	v_fmac_f32_e32 v147, v122, v122
	v_fmac_f32_e32 v147, v123, v123
	v_fmac_f32_e32 v147, v124, v124
	v_fmac_f32_e32 v147, v125, v125
	s_waitcnt vmcnt(15)
	v_mov_b32_e32 v148, v162
	v_mov_b32_e32 v149, v163
	v_mov_b32_e32 v150, v164
	v_mov_b32_e32 v151, v165
	v_lshlrev_b32_e32 v122, 16, v148
	v_and_b32_e32 v123, 0xffff0000, v148
	v_lshlrev_b32_e32 v124, 16, v149
	v_and_b32_e32 v125, 0xffff0000, v149
	v_pk_add_f32 v[118:119], v[118:119], v[122:123]
	v_pk_add_f32 v[124:125], v[120:121], v[124:125]
	v_mul_f32_e32 v120, v119, v119
	v_fmac_f32_e32 v120, v118, v118
	v_lshlrev_b32_e32 v128, 16, v150
	v_and_b32_e32 v129, 0xffff0000, v150
	v_fmac_f32_e32 v120, v124, v124
	v_pk_add_f32 v[114:115], v[114:115], v[128:129]
	v_fmac_f32_e32 v120, v125, v125
	v_lshlrev_b32_e32 v142, 16, v151
	v_and_b32_e32 v143, 0xffff0000, v151
	v_fmac_f32_e32 v120, v114, v114
	v_pk_add_f32 v[116:117], v[116:117], v[142:143]
	v_fmac_f32_e32 v120, v115, v115
	v_fmac_f32_e32 v120, v116, v116
	v_fmac_f32_e32 v120, v117, v117
	v_add_f32_e32 v128, v147, v120
	ds_bpermute_b32 v129, v126, v128
	v_cvt_pk_bf16_f32 v120, v118, v119
	v_cvt_pk_bf16_f32 v123, v116, v117
	v_lshlrev_b32_e32 v117, 2, v127
	v_or_b32_e32 v116, 0x100, v0
	s_waitcnt lgkmcnt(0)
	v_add_f32_e32 v118, v128, v129
	ds_bpermute_b32 v119, v117, v118
	v_cvt_pk_bf16_f32 v122, v114, v115
	v_or_b32_e32 v114, v116, v146
	v_cvt_pk_bf16_f32 v121, v124, v125
	buffer_store_dwordx4 v[120:123], v114, s[60:63], 0 offen
	v_lshl_add_u64 v[114:115], v[130:131], 3, s[16:17]
	s_and_saveexec_b64 s[0:1], vcc
	s_cbranch_execz .LBB0_646
	s_waitcnt lgkmcnt(0)
	v_add_f32_e32 v118, v118, v119
	v_mul_f32_e32 v118, 0x49800000, v118
	v_trunc_f32_e32 v118, v118
	v_mul_f32_e32 v119, 0x2f800000, v118
	v_floor_f32_e32 v119, v119
	v_fmac_f32_e32 v118, 0xcf800000, v119
	v_cvt_u32_f32_e32 v118, v118
	v_cvt_u32_f32_e32 v119, v119
	global_atomic_add_x2 v[114:115], v[118:119], off

; #define PG8_STAGE(bufoff, gbase, voff) do { _Pragma("unroll") for (int _i = 0; _i < 2; ++_i) \
;         __builtin_amdgcn_global_load_lds((const unsigned*)((const char*)(gbase) + (voff)[_i]), (LAS unsigned*)(lds + (bufoff) + ldsw + _i * 8192), 16, 0, 0); } while (0)
; #define PG8_LDA(dst, b, h) do { _Pragma("unroll") for (int m = 0; m < 4; ++m) _Pragma("unroll") for (int k = 0; k < 2; ++k) dst[m][k] = *(const LAS bf16x8*)(lds + PG8_SA(b, h) + aoff + m * 2048 + k * 1024); } while (0)
; #define PG8_LDB(dst, b, h) do { _Pragma("unroll") for (int n = 0; n < 2; ++n) _Pragma("unroll") for (int k = 0; k < 2; ++k) dst[n][k] = *(const LAS bf16x8*)(lds + PG8_SB(b, h) + boff + n * 2048 + k * 1024); } while (0)
; #define PG8_MMA(ai, bj, At, Bt) do { __builtin_amdgcn_s_setprio(1); _Pragma("unroll") for (int m = 0; m < 4; ++m) _Pragma("unroll") for (int n = 0; n < 2; ++n) _Pragma("unroll") for (int k = 0; k < 2; ++k) \
;         acc[ai][bj][m][n] = __builtin_amdgcn_mfma_f32_16x16x32_bf16(Bt[n][k], At[m][k], acc[ai][bj][m][n], 0, 0, 0); __builtin_amdgcn_s_setprio(0); } while (0)
; #define PG8_WAIT_L(n) asm volatile("s_waitcnt lgkmcnt(" #n ")" ::: "memory")
; #define PG8_BAR __builtin_amdgcn_s_barrier()
; #define PG8_SCHED __builtin_amdgcn_sched_barrier(0)
; template <int MODE>
; __device__ __forceinline__ void gemm_phase(LAS unsigned char* lds, const Params& p, int l, int single) {
;     ...
;             const bool last = (t == nt - 2);
;             const char* a1 = cA + (size_t)(t + 1) * kstep;
;             const char* a2 = last ? nA : cA + (size_t)(t + 2) * kstep; const char* b2 = last ? nB : cB + (size_t)(t + 2) * kstep;
;             const char* a3 = a2 + kstep; const char* b3 = b2 + kstep;
;             PG8_LDB(B0, 0, 0); PG8_SCHED; PG8_LDA(At, 0, 0); PG8_STAGE(PG8_SA(1, 1), a1 + hstep, voffA);
;             PG8_WAIT_L(8); PG8_BAR; PG8_WAIT_L(0); PG8_MMA(0, 0, At, B0); PG8_BAR; PG8_SCHED;
;             PG8_LDB(B1, 0, 1); PG8_STAGE(PG8_SB(0, 0), b2, voffB);
;             PG8_BAR; PG8_WAIT_L(0); PG8_MMA(0, 1, At, B1); PG8_BAR;
;             PG8_LDA(At, 0, 1); PG8_STAGE(PG8_SA(0, 0), a2, voffA);
;             PG8_BAR; PG8_WAIT_L(0); PG8_MMA(1, 0, At, B0); PG8_BAR; PG8_SCHED;
.LBB0_840:
	s_add_u32 s20, s18, 0xfff80080
	s_addc_u32 s21, s19, -1
	s_add_i32 s96, 0, 0x10000
	v_add_u32_e32 v142, s96, v162
	ds_read_b128 v[156:159], v142
	ds_read_b128 v[164:167], v142 offset:1024
	ds_read_b128 v[168:171], v142 offset:2048
	ds_read_b128 v[172:175], v142 offset:3072
	s_cmp_eq_u32 s85, 28
	s_cselect_b32 vcc_hi, s11, s21
	s_cselect_b32 vcc_lo, s13, s20
	s_cselect_b32 s21, s15, s84
	s_cselect_b32 s20, s24, s33
	v_lshl_add_u64 v[142:143], s[18:19], 0, v[152:153]
	s_add_i32 m0, s25, 0xc000
	ds_read_b128 v[176:179], v163
	ds_read_b128 v[180:183], v163 offset:1024
	ds_read_b128 v[184:187], v163 offset:2048
	ds_read_b128 v[188:191], v163 offset:3072
	ds_read_b128 v[192:195], v163 offset:4096
	ds_read_b128 v[196:199], v163 offset:5120
	ds_read_b128 v[208:211], v163 offset:6144
	ds_read_b128 v[212:215], v163 offset:7168
	global_load_lds_dwordx4 v[142:143], off
	v_lshl_add_u64 v[142:143], s[18:19], 0, v[154:155]
	s_add_i32 m0, s25, 0xe000
	s_nop 0
	global_load_lds_dwordx4 v[142:143], off
	s_waitcnt lgkmcnt(8)
	s_barrier
	s_waitcnt lgkmcnt(0)
	s_waitcnt lgkmcnt(0)
	v_mfma_f32_16x16x32_bf16 v[126:129], v[156:159], v[176:179], v[126:129]
	v_mfma_f32_16x16x32_bf16 v[122:125], v[168:171], v[176:179], v[122:125]
	v_mfma_f32_16x16x32_bf16 v[110:113], v[156:159], v[184:187], v[110:113]
	v_mfma_f32_16x16x32_bf16 v[106:109], v[168:171], v[184:187], v[106:109]
	v_mfma_f32_16x16x32_bf16 v[94:97], v[156:159], v[192:195], v[94:97]
	v_mfma_f32_16x16x32_bf16 v[90:93], v[168:171], v[192:195], v[90:93]
	v_mfma_f32_16x16x32_bf16 v[78:81], v[156:159], v[208:211], v[78:81]
	v_mfma_f32_16x16x32_bf16 v[74:77], v[168:171], v[208:211], v[74:77]
	v_mfma_f32_16x16x32_bf16 v[126:129], v[164:167], v[180:183], v[126:129]
	v_mfma_f32_16x16x32_bf16 v[122:125], v[172:175], v[180:183], v[122:125]
	v_mfma_f32_16x16x32_bf16 v[110:113], v[164:167], v[188:191], v[110:113]
	v_mfma_f32_16x16x32_bf16 v[106:109], v[172:175], v[188:191], v[106:109]
	v_mfma_f32_16x16x32_bf16 v[94:97], v[164:167], v[196:199], v[94:97]
	v_mfma_f32_16x16x32_bf16 v[90:93], v[172:175], v[196:199], v[90:93]
	v_mfma_f32_16x16x32_bf16 v[78:81], v[164:167], v[212:215], v[78:81]
	v_mfma_f32_16x16x32_bf16 v[74:77], v[172:175], v[212:215], v[74:77]
	s_barrier
	s_add_i32 s22, 0, 0x14000
	v_add_u32_e32 v142, s22, v162
	s_add_i32 s96, s96, s23
	ds_read_b128 v[216:219], v142
	ds_read_b128 v[220:223], v142 offset:1024
	ds_read_b128 v[224:227], v142 offset:2048
	ds_read_b128 v[228:231], v142 offset:3072
	v_lshl_add_u64 v[142:143], s[20:21], 0, v[0:1]
	s_mov_b32 m0, s96
	v_lshl_add_u64 v[160:161], s[20:21], 0, v[130:131]
	global_load_lds_dwordx4 v[142:143], off
	s_add_i32 m0, s96, 0x2000
	s_nop 0
	global_load_lds_dwordx4 v[160:161], off
	s_barrier
	s_waitcnt lgkmcnt(0)
	s_waitcnt lgkmcnt(0)
	v_mfma_f32_16x16x32_bf16 v[118:121], v[216:219], v[176:179], v[118:121]
	v_mfma_f32_16x16x32_bf16 v[114:117], v[224:227], v[176:179], v[114:117]
	v_mfma_f32_16x16x32_bf16 v[102:105], v[216:219], v[184:187], v[102:105]
	v_mfma_f32_16x16x32_bf16 v[98:101], v[224:227], v[184:187], v[98:101]
	v_mfma_f32_16x16x32_bf16 v[86:89], v[216:219], v[192:195], v[86:89]
	v_mfma_f32_16x16x32_bf16 v[82:85], v[224:227], v[192:195], v[82:85]
	v_mfma_f32_16x16x32_bf16 v[70:73], v[216:219], v[208:211], v[70:73]
	v_mfma_f32_16x16x32_bf16 v[66:69], v[224:227], v[208:211], v[66:69]
	v_mfma_f32_16x16x32_bf16 v[118:121], v[220:223], v[180:183], v[118:121]
	v_mfma_f32_16x16x32_bf16 v[114:117], v[228:231], v[180:183], v[114:117]
	v_mfma_f32_16x16x32_bf16 v[102:105], v[220:223], v[188:191], v[102:105]
	v_mfma_f32_16x16x32_bf16 v[98:101], v[228:231], v[188:191], v[98:101]
	v_mfma_f32_16x16x32_bf16 v[86:89], v[220:223], v[196:199], v[86:89]
	v_mfma_f32_16x16x32_bf16 v[82:85], v[228:231], v[196:199], v[82:85]
	v_mfma_f32_16x16x32_bf16 v[70:73], v[220:223], v[212:215], v[70:73]
	v_mfma_f32_16x16x32_bf16 v[66:69], v[228:231], v[212:215], v[66:69]
	s_mov_b32 m0, s25
	v_lshl_add_u64 v[232:233], vcc, 0, v[146:147]
	s_barrier
	ds_read_b128 v[176:179], v163 offset:16384
	ds_read_b128 v[180:183], v163 offset:17408
	ds_read_b128 v[184:187], v163 offset:18432
	ds_read_b128 v[188:191], v163 offset:19456
	ds_read_b128 v[192:195], v163 offset:20480
	ds_read_b128 v[196:199], v163 offset:21504
	ds_read_b128 v[208:211], v163 offset:22528
	ds_read_b128 v[212:215], v163 offset:23552
	global_load_lds_dwordx4 v[232:233], off
	v_lshl_add_u64 v[234:235], vcc, 0, v[132:133]
	s_mov_b32 m0, s28
	s_nop 0
	global_load_lds_dwordx4 v[234:235], off
	s_barrier
	s_waitcnt lgkmcnt(0)
	s_waitcnt lgkmcnt(0)
	v_mfma_f32_16x16x32_bf16 v[62:65], v[156:159], v[176:179], v[62:65]
	v_mfma_f32_16x16x32_bf16 v[58:61], v[168:171], v[176:179], v[58:61]
	v_mfma_f32_16x16x32_bf16 v[46:49], v[156:159], v[184:187], v[46:49]
	v_mfma_f32_16x16x32_bf16 v[42:45], v[168:171], v[184:187], v[42:45]
	v_mfma_f32_16x16x32_bf16 v[30:33], v[156:159], v[192:195], v[30:33]
	v_mfma_f32_16x16x32_bf16 v[26:29], v[168:171], v[192:195], v[26:29]
	v_mfma_f32_16x16x32_bf16 v[14:17], v[156:159], v[208:211], v[14:17]
	v_mfma_f32_16x16x32_bf16 v[10:13], v[168:171], v[208:211], v[10:13]
	v_mfma_f32_16x16x32_bf16 v[62:65], v[164:167], v[180:183], v[62:65]
	v_mfma_f32_16x16x32_bf16 v[58:61], v[172:175], v[180:183], v[58:61]
	v_mfma_f32_16x16x32_bf16 v[46:49], v[164:167], v[188:191], v[46:49]
	v_mfma_f32_16x16x32_bf16 v[42:45], v[172:175], v[188:191], v[42:45]
	v_mfma_f32_16x16x32_bf16 v[30:33], v[164:167], v[196:199], v[30:33]
	v_mfma_f32_16x16x32_bf16 v[26:29], v[172:175], v[196:199], v[26:29]
	v_mfma_f32_16x16x32_bf16 v[14:17], v[164:167], v[212:215], v[14:17]
	v_mfma_f32_16x16x32_bf16 v[10:13], v[172:175], v[212:215], v[10:13]
	s_barrier
; #define PG8_STAGE(bufoff, gbase, voff) do { _Pragma("unroll") for (int _i = 0; _i < 2; ++_i) \
;         __builtin_amdgcn_global_load_lds((const unsigned*)((const char*)(gbase) + (voff)[_i]), (LAS unsigned*)(lds + (bufoff) + ldsw + _i * 8192), 16, 0, 0); } while (0)
; #define PG8_LDA(dst, b, h) do { _Pragma("unroll") for (int m = 0; m < 4; ++m) _Pragma("unroll") for (int k = 0; k < 2; ++k) dst[m][k] = *(const LAS bf16x8*)(lds + PG8_SA(b, h) + aoff + m * 2048 + k * 1024); } while (0)
; #define PG8_LDB(dst, b, h) do { _Pragma("unroll") for (int n = 0; n < 2; ++n) _Pragma("unroll") for (int k = 0; k < 2; ++k) dst[n][k] = *(const LAS bf16x8*)(lds + PG8_SB(b, h) + boff + n * 2048 + k * 1024); } while (0)
; #define PG8_MMA(ai, bj, At, Bt) do { __builtin_amdgcn_s_setprio(1); _Pragma("unroll") for (int m = 0; m < 4; ++m) _Pragma("unroll") for (int n = 0; n < 2; ++n) _Pragma("unroll") for (int k = 0; k < 2; ++k) \
;         acc[ai][bj][m][n] = __builtin_amdgcn_mfma_f32_16x16x32_bf16(Bt[n][k], At[m][k], acc[ai][bj][m][n], 0, 0, 0); __builtin_amdgcn_s_setprio(0); } while (0)
; #define PG8_WAIT_V(n) asm volatile("s_waitcnt vmcnt(" #n ")" ::: "memory")
; #define PG8_WAIT_L(n) asm volatile("s_waitcnt lgkmcnt(" #n ")" ::: "memory")
; #define PG8_BAR __builtin_amdgcn_s_barrier()
; #define PG8_SCHED __builtin_amdgcn_sched_barrier(0)
; template <int MODE>
; __device__ __forceinline__ void gemm_phase(LAS unsigned char* lds, const Params& p, int l, int single) {
;     ...
;             PG8_STAGE(PG8_SB(0, 1), b2 + hstep, voffB);
;             PG8_WAIT_V(6); PG8_BAR; PG8_MMA(1, 1, At, B1); PG8_BAR;
;             PG8_LDB(B0, 1, 0); PG8_SCHED; PG8_LDA(At, 1, 0); PG8_STAGE(PG8_SA(0, 1), a2 + hstep, voffA);
;             PG8_WAIT_L(8); PG8_BAR; PG8_WAIT_L(0); PG8_MMA(0, 0, At, B0); PG8_BAR; PG8_SCHED;
;             PG8_LDB(B1, 1, 1); PG8_STAGE(PG8_SB(1, 0), b3, voffB);
;             PG8_BAR; PG8_WAIT_L(0); PG8_MMA(0, 1, At, B1); PG8_BAR;
;             PG8_LDA(At, 1, 1); PG8_STAGE(PG8_SA(1, 0), a3, voffA);
	s_add_u32 s96, s20, 0x80000
	s_addc_u32 s97, s21, 0
	s_add_i32 s22, s22, s23
	v_lshl_add_u64 v[156:157], s[96:97], 0, v[0:1]
	s_mov_b32 m0, s22
	s_nop 0
	global_load_lds_dwordx4 v[156:157], off
	v_lshl_add_u64 v[156:157], s[96:97], 0, v[130:131]
	s_add_i32 m0, s22, 0x2000
	s_nop 0
	global_load_lds_dwordx4 v[156:157], off
	s_waitcnt vmcnt(6)
	s_barrier
	v_mfma_f32_16x16x32_bf16 v[54:57], v[216:219], v[176:179], v[54:57]
	v_mfma_f32_16x16x32_bf16 v[50:53], v[224:227], v[176:179], v[50:53]
	v_mfma_f32_16x16x32_bf16 v[38:41], v[216:219], v[184:187], v[38:41]
	v_mfma_f32_16x16x32_bf16 v[34:37], v[224:227], v[184:187], v[34:37]
	v_mfma_f32_16x16x32_bf16 v[22:25], v[216:219], v[192:195], v[22:25]
	v_mfma_f32_16x16x32_bf16 v[18:21], v[224:227], v[192:195], v[18:21]
	v_mfma_f32_16x16x32_bf16 v[6:9], v[216:219], v[208:211], v[6:9]
	v_mfma_f32_16x16x32_bf16 v[2:5], v[224:227], v[208:211], v[2:5]
	v_mfma_f32_16x16x32_bf16 v[54:57], v[220:223], v[180:183], v[54:57]
	v_mfma_f32_16x16x32_bf16 v[50:53], v[228:231], v[180:183], v[50:53]
	v_mfma_f32_16x16x32_bf16 v[38:41], v[220:223], v[188:191], v[38:41]
	v_mfma_f32_16x16x32_bf16 v[34:37], v[228:231], v[188:191], v[34:37]
	v_mfma_f32_16x16x32_bf16 v[22:25], v[220:223], v[196:199], v[22:25]
	v_mfma_f32_16x16x32_bf16 v[18:21], v[228:231], v[196:199], v[18:21]
	v_mfma_f32_16x16x32_bf16 v[6:9], v[220:223], v[212:215], v[6:9]
	v_mfma_f32_16x16x32_bf16 v[2:5], v[228:231], v[212:215], v[2:5]
	s_add_i32 s22, 0, 0x18000
	v_add_u32_e32 v172, s22, v162
	s_barrier
	ds_read_b128 v[156:159], v172
	ds_read_b128 v[164:167], v172 offset:1024
	ds_read_b128 v[168:171], v172 offset:2048
	ds_read_b128 v[172:175], v172 offset:3072
	s_add_u32 s96, vcc_lo, 0x80000
	s_addc_u32 s97, vcc_hi, 0
	s_mov_b32 m0, s29
	v_lshl_add_u64 v[216:217], s[96:97], 0, v[146:147]
	ds_read_b128 v[176:179], v163 offset:32768
	ds_read_b128 v[180:183], v163 offset:33792
	ds_read_b128 v[184:187], v163 offset:34816
	ds_read_b128 v[188:191], v163 offset:35840
	ds_read_b128 v[192:195], v163 offset:36864
	ds_read_b128 v[196:199], v163 offset:37888
	ds_read_b128 v[208:211], v163 offset:38912
	ds_read_b128 v[212:215], v163 offset:39936
	global_load_lds_dwordx4 v[216:217], off
	v_lshl_add_u64 v[216:217], s[96:97], 0, v[132:133]
	s_mov_b32 m0, s76
	s_nop 0
	global_load_lds_dwordx4 v[216:217], off
	s_waitcnt lgkmcnt(8)
	s_barrier
	s_waitcnt lgkmcnt(0)
	s_waitcnt lgkmcnt(0)
	v_mfma_f32_16x16x32_bf16 v[126:129], v[156:159], v[176:179], v[126:129]
	v_mfma_f32_16x16x32_bf16 v[122:125], v[168:171], v[176:179], v[122:125]
	v_mfma_f32_16x16x32_bf16 v[110:113], v[156:159], v[184:187], v[110:113]
	v_mfma_f32_16x16x32_bf16 v[106:109], v[168:171], v[184:187], v[106:109]
	v_mfma_f32_16x16x32_bf16 v[94:97], v[156:159], v[192:195], v[94:97]
	v_mfma_f32_16x16x32_bf16 v[90:93], v[168:171], v[192:195], v[90:93]
	v_mfma_f32_16x16x32_bf16 v[78:81], v[156:159], v[208:211], v[78:81]
	v_mfma_f32_16x16x32_bf16 v[74:77], v[168:171], v[208:211], v[74:77]
	v_mfma_f32_16x16x32_bf16 v[126:129], v[164:167], v[180:183], v[126:129]
	v_mfma_f32_16x16x32_bf16 v[122:125], v[172:175], v[180:183], v[122:125]
	v_mfma_f32_16x16x32_bf16 v[110:113], v[164:167], v[188:191], v[110:113]
	v_mfma_f32_16x16x32_bf16 v[106:109], v[172:175], v[188:191], v[106:109]
	v_mfma_f32_16x16x32_bf16 v[94:97], v[164:167], v[196:199], v[94:97]
	v_mfma_f32_16x16x32_bf16 v[90:93], v[172:175], v[196:199], v[90:93]
	v_mfma_f32_16x16x32_bf16 v[78:81], v[164:167], v[212:215], v[78:81]
	v_mfma_f32_16x16x32_bf16 v[74:77], v[172:175], v[212:215], v[74:77]
	s_barrier
	s_add_i32 s96, 0, 0x1c000
	s_add_i32 s22, s22, s23
	v_add_u32_e32 v207, s96, v162
	v_lshl_add_u64 v[142:143], v[142:143], 0, s[94:95]
	s_mov_b32 m0, s22
	ds_read_b128 v[216:219], v207
	ds_read_b128 v[220:223], v207 offset:1024
	ds_read_b128 v[224:227], v207 offset:2048
	ds_read_b128 v[228:231], v207 offset:3072
	global_load_lds_dwordx4 v[142:143], off
	v_lshl_add_u64 v[142:143], v[160:161], 0, s[94:95]
	s_add_i32 m0, s22, 0x2000
	s_nop 0
	global_load_lds_dwordx4 v[142:143], off
	s_barrier
	s_waitcnt lgkmcnt(0)
	s_waitcnt lgkmcnt(0)
	v_mfma_f32_16x16x32_bf16 v[118:121], v[216:219], v[176:179], v[118:121]
	v_mfma_f32_16x16x32_bf16 v[114:117], v[224:227], v[176:179], v[114:117]
	v_mfma_f32_16x16x32_bf16 v[102:105], v[216:219], v[184:187], v[102:105]
	v_mfma_f32_16x16x32_bf16 v[98:101], v[224:227], v[184:187], v[98:101]
	v_mfma_f32_16x16x32_bf16 v[86:89], v[216:219], v[192:195], v[86:89]
	v_mfma_f32_16x16x32_bf16 v[82:85], v[224:227], v[192:195], v[82:85]
	v_mfma_f32_16x16x32_bf16 v[70:73], v[216:219], v[208:211], v[70:73]
	v_mfma_f32_16x16x32_bf16 v[66:69], v[224:227], v[208:211], v[66:69]
	v_mfma_f32_16x16x32_bf16 v[118:121], v[220:223], v[180:183], v[118:121]
	v_mfma_f32_16x16x32_bf16 v[114:117], v[228:231], v[180:183], v[114:117]
	v_mfma_f32_16x16x32_bf16 v[102:105], v[220:223], v[188:191], v[102:105]
	v_mfma_f32_16x16x32_bf16 v[98:101], v[228:231], v[188:191], v[98:101]
	v_mfma_f32_16x16x32_bf16 v[86:89], v[220:223], v[196:199], v[86:89]
	v_mfma_f32_16x16x32_bf16 v[82:85], v[228:231], v[196:199], v[82:85]
	v_mfma_f32_16x16x32_bf16 v[70:73], v[220:223], v[212:215], v[70:73]
	v_mfma_f32_16x16x32_bf16 v[66:69], v[228:231], v[212:215], v[66:69]
	s_mov_b32 m0, s90
	v_lshl_add_u64 v[142:143], v[232:233], 0, s[94:95]
	s_barrier
	ds_read_b128 v[176:179], v163 offset:49152
	ds_read_b128 v[180:183], v163 offset:50176
	ds_read_b128 v[184:187], v163 offset:51200
	ds_read_b128 v[188:191], v163 offset:52224
	ds_read_b128 v[192:195], v163 offset:53248
	ds_read_b128 v[196:199], v163 offset:54272
	ds_read_b128 v[208:211], v163 offset:55296
	ds_read_b128 v[212:215], v163 offset:56320
	global_load_lds_dwordx4 v[142:143], off
	v_lshl_add_u64 v[142:143], v[234:235], 0, s[94:95]
	s_mov_b32 m0, s6
	s_nop 0
	global_load_lds_dwordx4 v[142:143], off
	s_barrier
; #define PG8_STAGE(bufoff, gbase, voff) do { _Pragma("unroll") for (int _i = 0; _i < 2; ++_i) \
;         __builtin_amdgcn_global_load_lds((const unsigned*)((const char*)(gbase) + (voff)[_i]), (LAS unsigned*)(lds + (bufoff) + ldsw + _i * 8192), 16, 0, 0); } while (0)
; #define PG8_MMA(ai, bj, At, Bt) do { __builtin_amdgcn_s_setprio(1); _Pragma("unroll") for (int m = 0; m < 4; ++m) _Pragma("unroll") for (int n = 0; n < 2; ++n) _Pragma("unroll") for (int k = 0; k < 2; ++k) \
;         acc[ai][bj][m][n] = __builtin_amdgcn_mfma_f32_16x16x32_bf16(Bt[n][k], At[m][k], acc[ai][bj][m][n], 0, 0, 0); __builtin_amdgcn_s_setprio(0); } while (0)
; #define PG8_WAIT_V(n) asm volatile("s_waitcnt vmcnt(" #n ")" ::: "memory")
; #define PG8_WAIT_L(n) asm volatile("s_waitcnt lgkmcnt(" #n ")" ::: "memory")
; #define PG8_BAR __builtin_amdgcn_s_barrier()
; #define PG8_SCHED __builtin_amdgcn_sched_barrier(0)
; template <int MODE>
; __device__ __forceinline__ void gemm_phase(LAS unsigned char* lds, const Params& p, int l, int single) {
;     ...
;             PG8_BAR; PG8_WAIT_L(0); PG8_MMA(1, 0, At, B0); PG8_BAR; PG8_SCHED;
;             PG8_STAGE(PG8_SB(1, 1), b3 + hstep, voffB);
;             PG8_WAIT_V(6); PG8_BAR; PG8_MMA(1, 1, At, B1); PG8_BAR;
;         }
	s_waitcnt lgkmcnt(0)
	s_waitcnt lgkmcnt(0)
	v_mfma_f32_16x16x32_bf16 v[62:65], v[156:159], v[176:179], v[62:65]
	v_mfma_f32_16x16x32_bf16 v[58:61], v[168:171], v[176:179], v[58:61]
	v_mfma_f32_16x16x32_bf16 v[46:49], v[156:159], v[184:187], v[46:49]
	v_mfma_f32_16x16x32_bf16 v[42:45], v[168:171], v[184:187], v[42:45]
	v_mfma_f32_16x16x32_bf16 v[30:33], v[156:159], v[192:195], v[30:33]
	v_mfma_f32_16x16x32_bf16 v[26:29], v[168:171], v[192:195], v[26:29]
	v_mfma_f32_16x16x32_bf16 v[14:17], v[156:159], v[208:211], v[14:17]
	v_mfma_f32_16x16x32_bf16 v[10:13], v[168:171], v[208:211], v[10:13]
	v_mfma_f32_16x16x32_bf16 v[62:65], v[164:167], v[180:183], v[62:65]
	v_mfma_f32_16x16x32_bf16 v[58:61], v[172:175], v[180:183], v[58:61]
	v_mfma_f32_16x16x32_bf16 v[46:49], v[164:167], v[188:191], v[46:49]
	v_mfma_f32_16x16x32_bf16 v[42:45], v[172:175], v[188:191], v[42:45]
	v_mfma_f32_16x16x32_bf16 v[30:33], v[164:167], v[196:199], v[30:33]
	v_mfma_f32_16x16x32_bf16 v[26:29], v[172:175], v[196:199], v[26:29]
	v_mfma_f32_16x16x32_bf16 v[14:17], v[164:167], v[212:215], v[14:17]
	v_mfma_f32_16x16x32_bf16 v[10:13], v[172:175], v[212:215], v[10:13]
	s_barrier
	s_add_u32 s20, s20, 0x80080
	s_addc_u32 s21, s21, 0
	s_add_i32 s22, s96, s23
	v_lshl_add_u64 v[142:143], s[20:21], 0, v[0:1]
	s_mov_b32 m0, s22
	s_nop 0
	global_load_lds_dwordx4 v[142:143], off
	v_lshl_add_u64 v[142:143], s[20:21], 0, v[130:131]
	s_add_i32 m0, s22, 0x2000
	s_nop 0
	global_load_lds_dwordx4 v[142:143], off
	s_waitcnt vmcnt(6)
	s_barrier
	v_mfma_f32_16x16x32_bf16 v[54:57], v[216:219], v[176:179], v[54:57]
	v_mfma_f32_16x16x32_bf16 v[50:53], v[224:227], v[176:179], v[50:53]
	v_mfma_f32_16x16x32_bf16 v[38:41], v[216:219], v[184:187], v[38:41]
	v_mfma_f32_16x16x32_bf16 v[34:37], v[224:227], v[184:187], v[34:37]
	v_mfma_f32_16x16x32_bf16 v[22:25], v[216:219], v[192:195], v[22:25]
	v_mfma_f32_16x16x32_bf16 v[18:21], v[224:227], v[192:195], v[18:21]
	v_mfma_f32_16x16x32_bf16 v[6:9], v[216:219], v[208:211], v[6:9]
	v_mfma_f32_16x16x32_bf16 v[2:5], v[224:227], v[208:211], v[2:5]
	v_mfma_f32_16x16x32_bf16 v[54:57], v[220:223], v[180:183], v[54:57]
	v_mfma_f32_16x16x32_bf16 v[50:53], v[228:231], v[180:183], v[50:53]
	v_mfma_f32_16x16x32_bf16 v[38:41], v[220:223], v[188:191], v[38:41]
	v_mfma_f32_16x16x32_bf16 v[34:37], v[228:231], v[188:191], v[34:37]
	v_mfma_f32_16x16x32_bf16 v[22:25], v[220:223], v[196:199], v[22:25]
	v_mfma_f32_16x16x32_bf16 v[18:21], v[228:231], v[196:199], v[18:21]
	v_mfma_f32_16x16x32_bf16 v[6:9], v[220:223], v[212:215], v[6:9]
	v_mfma_f32_16x16x32_bf16 v[2:5], v[228:231], v[212:215], v[2:5]
	s_add_i32 s85, s85, 2
	s_add_u32 s18, s18, 0x100
	s_addc_u32 s19, s19, 0
	s_add_u32 s33, s33, 0x100
	s_addc_u32 s84, s84, 0
	s_cmp_gt_u32 s85, 29
	s_barrier
	s_cbranch_scc0 .LBB0_840
; __device__ __forceinline__ unsigned cvt_pk_bf16(float lo, float hi) { unsigned r; asm("v_cvt_pk_bf16_f32 %0, %1, %2" : "=v"(r) : "v"(lo), "v"(hi)); return r; }
; __device__ __forceinline__ float bflo(unsigned w) { return __uint_as_float(w << 16); }
; __device__ __forceinline__ float bfhi(unsigned w) { return __uint_as_float(w & 0xffff0000u); }
; #define WT_STORE16(ptr, val) __builtin_amdgcn_raw_buffer_store_b128((val), wsr, (int)((const char*)(ptr) - (const char*)ws), 0, 16)
; template <int MODE>
; __device__ __forceinline__ void gemm_epilogue(const Params& p, int l, const f32x4 (&acc)[2][2][4][2], const Unit& u, int wr, int wc, int fr, int fq, const LAS float* rl, int pm0) {
;     ...
;         u16* xb = (u16*)(ws + WS_XB);
;         u64* ssn = (u64*)(ws + WS_SUMSQ) + (size_t)(l + 1) * T;
; #pragma unroll
;         for (int ai = 0; ai < 2; ++ai)
; #pragma unroll
;             for (int m = 0; m < 4; ++m) {
;                 const int tok = u.pm * 256 + 128 * ai + 64 * wr + 16 * m + fr;
;                 float part = 0.f;
; #pragma unroll
;                 for (int bj = 0; bj < 2; ++bj) {
;                     const size_t idx = (size_t)tok * 2048 + u.pn * 256 + 128 * bj + 32 * wc + 8 * fq;
;                     const u32x4 xw = *(const u32x4*)(xb + idx);
;                     f32x4 y0 = (f32x4){bflo(xw.x), bfhi(xw.x), bflo(xw.y), bfhi(xw.y)}, y1 = (f32x4){bflo(xw.z), bfhi(xw.z), bflo(xw.w), bfhi(xw.w)};
;                     y0 += acc[ai][bj][m][0]; y1 += acc[ai][bj][m][1];
;                     part += y0[0] * y0[0] + y0[1] * y0[1] + y0[2] * y0[2] + y0[3] * y0[3] + y1[0] * y1[0] + y1[1] * y1[1] + y1[2] * y1[2] + y1[3] * y1[3];
;                     u32x4 w; w.x = cvt_pk_bf16(y0[0], y0[1]); w.y = cvt_pk_bf16(y0[2], y0[3]); w.z = cvt_pk_bf16(y1[0], y1[1]); w.w = cvt_pk_bf16(y1[2], y1[3]);
;                     WT_STORE16(xb + idx, w);
;                 }
;                 part += __shfl_xor(part, 16); part += __shfl_xor(part, 32);
;                 if (fq == 0) atomicAdd(ssn + tok, (u64)(part * SS_SCALE));
;             }
	v_lshl_add_u32 v158, s10, 8, v149
	s_lshl_b32 s10, s2, 8
	s_ashr_i32 s11, s10, 31
	v_ashrrev_i32_e32 v159, 31, v158
	v_lshl_add_u64 v[156:157], s[10:11], 1, v[150:151]
	v_mov_b32_e32 v178, v158
	v_ashrrev_i32_e32 v179, 31, v178
	v_lshlrev_b64 v[178:179], 12, v[178:179]
	v_lshl_add_u64 v[178:179], v[156:157], 0, v[178:179]
	global_load_dwordx4 v[174:177], v[178:179], off
	global_load_dwordx4 v[178:181], v[178:179], off offset:256
	v_add_u32_e32 v186, 0x10, v158
	v_ashrrev_i32_e32 v187, 31, v186
	v_lshlrev_b64 v[186:187], 12, v[186:187]
	v_lshl_add_u64 v[186:187], v[156:157], 0, v[186:187]
	global_load_dwordx4 v[182:185], v[186:187], off
	global_load_dwordx4 v[186:189], v[186:187], off offset:256
	v_add_u32_e32 v194, 0x20, v158
	v_ashrrev_i32_e32 v195, 31, v194
	v_lshlrev_b64 v[194:195], 12, v[194:195]
	v_lshl_add_u64 v[194:195], v[156:157], 0, v[194:195]
	global_load_dwordx4 v[190:193], v[194:195], off
	global_load_dwordx4 v[194:197], v[194:195], off offset:256
	v_add_u32_e32 v212, 0x30, v158
	v_ashrrev_i32_e32 v213, 31, v212
	v_lshlrev_b64 v[212:213], 12, v[212:213]
	v_lshl_add_u64 v[212:213], v[156:157], 0, v[212:213]
	global_load_dwordx4 v[208:211], v[212:213], off
	global_load_dwordx4 v[212:215], v[212:213], off offset:256
	v_add_u32_e32 v220, 0x80, v158
	v_ashrrev_i32_e32 v221, 31, v220
	v_lshlrev_b64 v[220:221], 12, v[220:221]
	v_lshl_add_u64 v[220:221], v[156:157], 0, v[220:221]
	global_load_dwordx4 v[216:219], v[220:221], off
	global_load_dwordx4 v[220:223], v[220:221], off offset:256
	v_add_u32_e32 v228, 0x90, v158
	v_ashrrev_i32_e32 v229, 31, v228
	v_lshlrev_b64 v[228:229], 12, v[228:229]
	v_lshl_add_u64 v[228:229], v[156:157], 0, v[228:229]
	global_load_dwordx4 v[224:227], v[228:229], off
	global_load_dwordx4 v[228:231], v[228:229], off offset:256
	v_lshlrev_b64 v[142:143], 12, v[158:159]
	v_lshl_add_u64 v[168:169], v[156:157], 0, v[142:143]
	v_or_b32_e32 v160, s10, v148
	v_mov_b32_e32 v161, s11
	v_add_u32_e32 v172, 0x10800000, v142
	v_lshlrev_b64 v[160:161], 1, v[160:161]
	v_add_u32_e32 v161, v172, v160
	v_readlane_b32 s10, v252, 45
	v_readlane_b32 s11, v252, 46
	s_waitcnt vmcnt(11)
	v_mov_b32_e32 v164, v174
	v_mov_b32_e32 v165, v175
	v_mov_b32_e32 v166, v176
	v_mov_b32_e32 v167, v177
	v_lshlrev_b32_e32 v142, 16, v164
	v_and_b32_e32 v143, 0xffff0000, v164
	v_lshlrev_b32_e32 v164, 16, v165
	v_and_b32_e32 v165, 0xffff0000, v165
	v_lshlrev_b32_e32 v170, 16, v166
	v_and_b32_e32 v171, 0xffff0000, v166
	v_lshlrev_b32_e32 v166, 16, v167
	v_and_b32_e32 v167, 0xffff0000, v167
	v_pk_add_f32 v[128:129], v[128:129], v[164:165]
	v_pk_add_f32 v[142:143], v[126:127], v[142:143]
	v_pk_add_f32 v[164:165], v[124:125], v[166:167]
	v_pk_add_f32 v[166:167], v[122:123], v[170:171]
	v_cvt_pk_bf16_f32 v122, v142, v143
	v_cvt_pk_bf16_f32 v123, v128, v129
	v_cvt_pk_bf16_f32 v125, v164, v165
	s_nop 0
	v_cvt_pk_bf16_f32 v124, v166, v167
	buffer_store_dwordx4 v[122:125], v161, s[60:63], 0 offen
	v_xor_b32_e32 v161, 32, v205
	v_and_b32_e32 v123, 64, v205
	v_xor_b32_e32 v122, 16, v205
	v_add_u32_e32 v123, 64, v123
	v_cmp_lt_i32_e32 vcc, v122, v123
	s_nop 1
	v_cndmask_b32_e32 v122, v205, v122, vcc
	v_cmp_lt_i32_e32 vcc, v161, v123
	v_lshlrev_b32_e32 v122, 2, v122
	s_nop 0
	v_cndmask_b32_e32 v123, v205, v161, vcc
	v_mul_f32_e32 v161, v143, v143
	v_fmac_f32_e32 v161, v142, v142
	v_fmac_f32_e32 v161, v128, v128
	v_fmac_f32_e32 v161, v129, v129
	v_fmac_f32_e32 v161, v166, v166
	v_fmac_f32_e32 v161, v167, v167
	v_fmac_f32_e32 v161, v164, v164
	v_fmac_f32_e32 v161, v165, v165
	s_waitcnt vmcnt(11)
	v_mov_b32_e32 v124, v178
	v_mov_b32_e32 v125, v179
	v_mov_b32_e32 v126, v180
	v_mov_b32_e32 v127, v181
	v_add_u32_e32 v178, 0xa0, v158
	v_ashrrev_i32_e32 v179, 31, v178
	v_lshlrev_b64 v[178:179], 12, v[178:179]
	v_lshl_add_u64 v[178:179], v[156:157], 0, v[178:179]
	global_load_dwordx4 v[174:177], v[178:179], off
	global_load_dwordx4 v[178:181], v[178:179], off offset:256
	v_lshlrev_b32_e32 v128, 16, v124
	v_and_b32_e32 v129, 0xffff0000, v124
	v_lshlrev_b32_e32 v124, 16, v125
	v_and_b32_e32 v125, 0xffff0000, v125
	v_pk_add_f32 v[118:119], v[118:119], v[128:129]
	v_pk_add_f32 v[120:121], v[120:121], v[124:125]
	v_mul_f32_e32 v124, v119, v119
	v_fmac_f32_e32 v124, v118, v118
	v_lshlrev_b32_e32 v142, 16, v126
	v_and_b32_e32 v143, 0xffff0000, v126
	v_fmac_f32_e32 v124, v120, v120
	v_pk_add_f32 v[114:115], v[114:115], v[142:143]
	v_fmac_f32_e32 v124, v121, v121
	v_lshlrev_b32_e32 v126, 16, v127
	v_and_b32_e32 v127, 0xffff0000, v127
	v_fmac_f32_e32 v124, v114, v114
	v_pk_add_f32 v[116:117], v[116:117], v[126:127]
	v_fmac_f32_e32 v124, v115, v115
	v_fmac_f32_e32 v124, v116, v116
	v_fmac_f32_e32 v124, v117, v117
	v_add_f32_e32 v128, v161, v124
	ds_bpermute_b32 v129, v122, v128
	v_cvt_pk_bf16_f32 v124, v118, v119
	v_cvt_pk_bf16_f32 v127, v116, v117
	v_lshlrev_b32_e32 v117, 2, v123
	v_or_b32_e32 v116, 0x100, v160
	s_waitcnt lgkmcnt(0)
	v_add_f32_e32 v118, v128, v129
	ds_bpermute_b32 v119, v117, v118
	v_cvt_pk_bf16_f32 v126, v114, v115
	v_add_u32_e32 v114, v172, v116
	v_cvt_pk_bf16_f32 v125, v120, v121
	buffer_store_dwordx4 v[124:127], v114, s[60:63], 0 offen
	v_lshl_add_u64 v[114:115], v[158:159], 3, s[10:11]
	s_and_saveexec_b64 s[18:19], s[38:39]
	s_cbranch_execz .LBB0_843
	s_waitcnt lgkmcnt(0)
	v_add_f32_e32 v118, v118, v119
	v_mul_f32_e32 v118, 0x49800000, v118
	v_trunc_f32_e32 v118, v118
	v_mul_f32_e32 v119, 0x2f800000, v118
	v_floor_f32_e32 v119, v119
	v_fmac_f32_e32 v118, 0xcf800000, v119
	v_cvt_u32_f32_e32 v118, v118
	v_cvt_u32_f32_e32 v119, v119
	global_atomic_add_x2 v[114:115], v[118:119], off
